# LDS-DMA 3-stage GEMM main loop for layer-1 in-projection + per-block rotated k-order in filter-tap reduction
# speedup vs baseline: 1.0808x; 1.0106x over previous
.LBB0_579:
	s_ashr_i32 s0, s2, 31
	s_lshr_b32 s1, s0, 26
	s_add_i32 s1, s2, s1
	s_ashr_i32 s22, s1, 6
	s_and_b32 s23, s1, 0xffc0
	s_lshr_b32 s1, s1, 31
	s_add_i32 s1, s22, s1
	s_sub_i32 s23, s2, s23
	s_and_b32 s1, s1, 0x1ffffe
	s_sub_i32 s1, s22, s1
	s_bfe_i32 s22, s23, 0x80000
	s_bfe_u32 s22, s22, 0x3000c
	s_lshr_b32 s0, s0, 25
	s_add_i32 s22, s23, s22
	s_add_i32 s0, s2, s0
	s_bfe_i32 s24, s22, 0x80000
	s_sext_i32_i16 s24, s24
	s_lshr_b32 s0, s0, 1
	s_and_b32 s0, s0, 0x1ffffc0
	s_and_b32 s24, s24, -8
	s_add_i32 s24, s24, s0
	v_readlane_b32 s0, v246, 0
	s_and_b32 s22, s22, 0xf8
	s_or_b32 s0, s24, s0
	s_sub_i32 s22, s23, s22
	s_sext_i32_i8 s23, s22
	s_lshl_b32 s22, s0, 7
	s_lshl_b32 s0, s1, 11
	s_lshl_b32 s23, s23, 8
	s_add_i32 s23, s23, s0
	s_barrier
	v_lshrrev_b32_e32 v226, 6, v184
	v_and_b32_e32 v227, 63, v184
	v_readfirstlane_b32 s6, v226
	v_lshrrev_b32_e32 v228, 2, v227
	v_bfe_u32 v229, v227, 4, 2
	v_and_b32_e32 v230, 3, v227
	v_xor_b32_e32 v229, v230, v229
	v_lshlrev_b32_e32 v229, 4, v229
	v_lshl_add_u32 v228, v228, 11, v229
	v_mov_b32_e32 v229, 0
	v_readlane_b32 s4, v246, 4
	v_readlane_b32 s5, v246, 5
	v_readlane_b32 s12, v246, 18
	v_readlane_b32 s13, v246, 19
	s_nop 3
	s_lshl_b32 s0, s6, 5
	s_add_i32 s0, s0, s22
	s_lshl_b32 s0, s0, 11
	s_add_u32 s4, s4, s0
	s_addc_u32 s5, s5, 0
	v_lshl_add_u64 v[202:203], v[228:229], 0, s[4:5]
	s_add_u32 s4, s4, 0x8000
	s_addc_u32 s5, s5, 0
	v_lshl_add_u64 v[204:205], v[228:229], 0, s[4:5]
	s_lshl_b32 s0, s6, 6
	s_add_i32 s0, s0, s23
	s_lshl_b32 s0, s0, 11
	s_add_u32 s12, s12, s0
	s_addc_u32 s13, s13, 0
	v_lshl_add_u64 v[206:207], v[228:229], 0, s[12:13]
	s_add_u32 s12, s12, 0x8000
	s_addc_u32 s13, s13, 0
	v_lshl_add_u64 v[208:209], v[228:229], 0, s[12:13]
	s_add_u32 s12, s12, 0x8000
	s_addc_u32 s13, s13, 0
	v_lshl_add_u64 v[210:211], v[228:229], 0, s[12:13]
	s_add_u32 s12, s12, 0x8000
	s_addc_u32 s13, s13, 0
	v_lshl_add_u64 v[212:213], v[228:229], 0, s[12:13]
	s_lshl_b32 s8, s6, 11
	s_lshl_b32 s9, s6, 12
	s_add_u32 s9, s9, 0x2000
	s_mov_b32 s10, 64
	s_mov_b32 s11, 0
	s_add_u32 m0, s8, 0x0
	s_nop 0
	global_load_lds_dwordx4 v[202:203], off
	v_lshl_add_u64 v[202:203], v[202:203], 0, s[10:11]
	s_add_u32 m0, s8, 0x400
	s_nop 0
	global_load_lds_dwordx4 v[204:205], off
	v_lshl_add_u64 v[204:205], v[204:205], 0, s[10:11]
	s_add_u32 m0, s9, 0x0
	s_nop 0
	global_load_lds_dwordx4 v[206:207], off
	v_lshl_add_u64 v[206:207], v[206:207], 0, s[10:11]
	s_add_u32 m0, s9, 0x400
	s_nop 0
	global_load_lds_dwordx4 v[208:209], off
	v_lshl_add_u64 v[208:209], v[208:209], 0, s[10:11]
	s_add_u32 m0, s9, 0x800
	s_nop 0
	global_load_lds_dwordx4 v[210:211], off
	v_lshl_add_u64 v[210:211], v[210:211], 0, s[10:11]
	s_add_u32 m0, s9, 0xc00
	s_nop 0
	global_load_lds_dwordx4 v[212:213], off
	v_lshl_add_u64 v[212:213], v[212:213], 0, s[10:11]
	s_add_u32 m0, s8, 0x6000
	s_nop 0
	global_load_lds_dwordx4 v[202:203], off
	v_lshl_add_u64 v[202:203], v[202:203], 0, s[10:11]
	s_add_u32 m0, s8, 0x6400
	s_nop 0
	global_load_lds_dwordx4 v[204:205], off
	v_lshl_add_u64 v[204:205], v[204:205], 0, s[10:11]
	s_add_u32 m0, s9, 0x6000
	s_nop 0
	global_load_lds_dwordx4 v[206:207], off
	v_lshl_add_u64 v[206:207], v[206:207], 0, s[10:11]
	s_add_u32 m0, s9, 0x6400
	s_nop 0
	global_load_lds_dwordx4 v[208:209], off
	v_lshl_add_u64 v[208:209], v[208:209], 0, s[10:11]
	s_add_u32 m0, s9, 0x6800
	s_nop 0
	global_load_lds_dwordx4 v[210:211], off
	v_lshl_add_u64 v[210:211], v[210:211], 0, s[10:11]
	s_add_u32 m0, s9, 0x6c00
	s_nop 0
	global_load_lds_dwordx4 v[212:213], off
	v_lshl_add_u64 v[212:213], v[212:213], 0, s[10:11]
	v_and_b32_e32 v230, 31, v227
	v_lshrrev_b32_e32 v238, 5, v227
	v_bfe_u32 v232, v230, 2, 2
	v_xor_b32_e32 v233, v238, v232
	v_xor_b32_e32 v234, 2, v233
	v_lshlrev_b32_e32 v233, 4, v233
	v_lshlrev_b32_e32 v234, 4, v234
	v_lshlrev_b32_e32 v235, 6, v230
	v_lshrrev_b32_e32 v236, 1, v226
	v_and_b32_e32 v237, 1, v226
	v_lshl_add_u32 v236, v236, 12, v235
	v_lshl_add_u32 v237, v237, 13, v235
	v_add_u32_e32 v237, 0x2000, v237
	v_add_u32_e32 v214, v233, v236
	v_add_u32_e32 v216, v233, v237
	v_add_u32_e32 v215, v234, v236
	v_add_u32_e32 v217, v234, v237
	v_add_u32_e32 v218, 0x6000, v214
	v_add_u32_e32 v220, 0x6000, v216
	v_add_u32_e32 v219, 0x6000, v215
	v_add_u32_e32 v221, 0x6000, v217
	v_add_u32_e32 v222, 0xc010, v214
	v_add_u32_e32 v224, 0xc010, v216
	v_add_u32_e32 v223, 0xc010, v215
	v_add_u32_e32 v225, 0xc010, v217
	v_mov_b32_e32 v2, 0
	v_mov_b32_e32 v3, v2
	v_mov_b32_e32 v4, v2
	v_mov_b32_e32 v5, v2
	v_mov_b32_e32 v6, v2
	v_mov_b32_e32 v7, v2
	v_mov_b32_e32 v8, v2
	v_mov_b32_e32 v9, v2
	v_mov_b32_e32 v10, v2
	v_mov_b32_e32 v11, v2
	v_mov_b32_e32 v12, v2
	v_mov_b32_e32 v13, v2
	v_mov_b32_e32 v14, v2
	v_mov_b32_e32 v15, v2
	v_mov_b32_e32 v16, v2
	v_mov_b32_e32 v17, v2
	v_mov_b32_e32 v18, v2
	v_mov_b32_e32 v19, v2
	v_mov_b32_e32 v20, v2
	v_mov_b32_e32 v21, v2
	v_mov_b32_e32 v22, v2
	v_mov_b32_e32 v23, v2
	v_mov_b32_e32 v24, v2
	v_mov_b32_e32 v25, v2
	v_mov_b32_e32 v26, v2
	v_mov_b32_e32 v27, v2
	v_mov_b32_e32 v28, v2
	v_mov_b32_e32 v29, v2
	v_mov_b32_e32 v30, v2
	v_mov_b32_e32 v31, v2
	v_mov_b32_e32 v32, v2
	v_mov_b32_e32 v33, v2
	v_mov_b32_e32 v34, v2
	v_mov_b32_e32 v35, v2
	v_mov_b32_e32 v36, v2
	v_mov_b32_e32 v37, v2
	v_mov_b32_e32 v38, v2
	v_mov_b32_e32 v39, v2
	v_mov_b32_e32 v40, v2
	v_mov_b32_e32 v41, v2
	v_mov_b32_e32 v42, v2
	v_mov_b32_e32 v43, v2
	v_mov_b32_e32 v44, v2
	v_mov_b32_e32 v45, v2
	v_mov_b32_e32 v46, v2
	v_mov_b32_e32 v47, v2
	v_mov_b32_e32 v48, v2
	v_mov_b32_e32 v49, v2
	v_mov_b32_e32 v50, v2
	v_mov_b32_e32 v51, v2
	v_mov_b32_e32 v52, v2
	v_mov_b32_e32 v53, v2
	v_mov_b32_e32 v54, v2
	v_mov_b32_e32 v55, v2
	v_mov_b32_e32 v56, v2
	v_mov_b32_e32 v57, v2
	v_mov_b32_e32 v58, v2
	v_mov_b32_e32 v59, v2
	v_mov_b32_e32 v60, v2
	v_mov_b32_e32 v61, v2
	v_mov_b32_e32 v62, v2
	v_mov_b32_e32 v63, v2
	v_mov_b32_e32 v64, v2
	v_mov_b32_e32 v65, v2
	v_mov_b32_e32 v66, v2
	v_mov_b32_e32 v67, v2
	v_mov_b32_e32 v68, v2
	v_mov_b32_e32 v69, v2
	v_mov_b32_e32 v70, v2
	v_mov_b32_e32 v71, v2
	v_mov_b32_e32 v72, v2
	v_mov_b32_e32 v73, v2
	v_mov_b32_e32 v74, v2
	v_mov_b32_e32 v75, v2
	v_mov_b32_e32 v76, v2
	v_mov_b32_e32 v77, v2
	v_mov_b32_e32 v78, v2
	v_mov_b32_e32 v79, v2
	v_mov_b32_e32 v80, v2
	v_mov_b32_e32 v81, v2
	v_mov_b32_e32 v82, v2
	v_mov_b32_e32 v83, v2
	v_mov_b32_e32 v84, v2
	v_mov_b32_e32 v85, v2
	v_mov_b32_e32 v86, v2
	v_mov_b32_e32 v87, v2
	v_mov_b32_e32 v88, v2
	v_mov_b32_e32 v89, v2
	v_mov_b32_e32 v90, v2
	v_mov_b32_e32 v91, v2
	v_mov_b32_e32 v92, v2
	v_mov_b32_e32 v93, v2
	v_mov_b32_e32 v94, v2
	v_mov_b32_e32 v95, v2
	v_mov_b32_e32 v96, v2
	v_mov_b32_e32 v97, v2
	v_mov_b32_e32 v98, v2
	v_mov_b32_e32 v99, v2
	v_mov_b32_e32 v100, v2
	v_mov_b32_e32 v101, v2
	v_mov_b32_e32 v102, v2
	v_mov_b32_e32 v103, v2
	v_mov_b32_e32 v104, v2
	v_mov_b32_e32 v105, v2
	v_mov_b32_e32 v106, v2
	v_mov_b32_e32 v107, v2
	v_mov_b32_e32 v108, v2
	v_mov_b32_e32 v109, v2
	v_mov_b32_e32 v110, v2
	v_mov_b32_e32 v111, v2
	v_mov_b32_e32 v112, v2
	v_mov_b32_e32 v113, v2
	v_mov_b32_e32 v114, v2
	v_mov_b32_e32 v115, v2
	v_mov_b32_e32 v116, v2
	v_mov_b32_e32 v117, v2
	v_mov_b32_e32 v118, v2
	v_mov_b32_e32 v119, v2
	v_mov_b32_e32 v120, v2
	v_mov_b32_e32 v121, v2
	v_mov_b32_e32 v122, v2
	v_mov_b32_e32 v123, v2
	v_mov_b32_e32 v124, v2
	v_mov_b32_e32 v125, v2
	v_mov_b32_e32 v126, v2
	v_mov_b32_e32 v127, v2
	v_mov_b32_e32 v128, v2
	v_mov_b32_e32 v129, v2
	s_mov_b32 s7, 10
.Lgemm_p7_loop:
	s_waitcnt vmcnt(6)
	s_barrier
	ds_read_b128 v[130:133], v214
	ds_read_b128 v[134:137], v214 offset:2048
	ds_read_b128 v[138:141], v216
	ds_read_b128 v[142:145], v216 offset:2048
	ds_read_b128 v[146:149], v216 offset:4096
	ds_read_b128 v[150:153], v216 offset:6144
	ds_read_b128 v[154:157], v215
	ds_read_b128 v[158:161], v215 offset:2048
	ds_read_b128 v[162:165], v217
	ds_read_b128 v[166:169], v217 offset:2048
	ds_read_b128 v[170:173], v217 offset:4096
	ds_read_b128 v[174:177], v217 offset:6144
	s_add_u32 m0, s8, 0xc010
	s_nop 0
	global_load_lds_dwordx4 v[202:203], off
	v_lshl_add_u64 v[202:203], v[202:203], 0, s[10:11]
	s_waitcnt lgkmcnt(9)
	v_mfma_f32_32x32x16_bf16 v[114:129], v[138:141], v[130:133], v[114:129]
	v_mfma_f32_32x32x16_bf16 v[98:113], v[138:141], v[134:137], v[98:113]
	s_add_u32 m0, s8, 0xc410
	s_nop 0
	global_load_lds_dwordx4 v[204:205], off
	v_lshl_add_u64 v[204:205], v[204:205], 0, s[10:11]
	s_waitcnt lgkmcnt(8)
	v_mfma_f32_32x32x16_bf16 v[82:97], v[142:145], v[130:133], v[82:97]
	v_mfma_f32_32x32x16_bf16 v[66:81], v[142:145], v[134:137], v[66:81]
	s_add_u32 m0, s9, 0xc010
	s_nop 0
	global_load_lds_dwordx4 v[206:207], off
	v_lshl_add_u64 v[206:207], v[206:207], 0, s[10:11]
	s_waitcnt lgkmcnt(7)
	v_mfma_f32_32x32x16_bf16 v[50:65], v[146:149], v[130:133], v[50:65]
	v_mfma_f32_32x32x16_bf16 v[34:49], v[146:149], v[134:137], v[34:49]
	s_add_u32 m0, s9, 0xc410
	s_nop 0
	global_load_lds_dwordx4 v[208:209], off
	v_lshl_add_u64 v[208:209], v[208:209], 0, s[10:11]
	s_waitcnt lgkmcnt(6)
	v_mfma_f32_32x32x16_bf16 v[18:33], v[150:153], v[130:133], v[18:33]
	v_mfma_f32_32x32x16_bf16 v[2:17], v[150:153], v[134:137], v[2:17]
	s_add_u32 m0, s9, 0xc810
	s_nop 0
	global_load_lds_dwordx4 v[210:211], off
	v_lshl_add_u64 v[210:211], v[210:211], 0, s[10:11]
	s_waitcnt lgkmcnt(3)
	v_mfma_f32_32x32x16_bf16 v[114:129], v[162:165], v[154:157], v[114:129]
	v_mfma_f32_32x32x16_bf16 v[98:113], v[162:165], v[158:161], v[98:113]
	s_add_u32 m0, s9, 0xcc10
	s_nop 0
	global_load_lds_dwordx4 v[212:213], off
	v_lshl_add_u64 v[212:213], v[212:213], 0, s[10:11]
	s_waitcnt lgkmcnt(2)
	v_mfma_f32_32x32x16_bf16 v[82:97], v[166:169], v[154:157], v[82:97]
	v_mfma_f32_32x32x16_bf16 v[66:81], v[166:169], v[158:161], v[66:81]
	s_waitcnt lgkmcnt(1)
	v_mfma_f32_32x32x16_bf16 v[50:65], v[170:173], v[154:157], v[50:65]
	v_mfma_f32_32x32x16_bf16 v[34:49], v[170:173], v[158:161], v[34:49]
	s_waitcnt lgkmcnt(0)
	v_mfma_f32_32x32x16_bf16 v[18:33], v[174:177], v[154:157], v[18:33]
	v_mfma_f32_32x32x16_bf16 v[2:17], v[174:177], v[158:161], v[2:17]
	s_waitcnt vmcnt(6)
	s_barrier
	ds_read_b128 v[130:133], v218
	ds_read_b128 v[134:137], v218 offset:2048
	ds_read_b128 v[138:141], v220
	ds_read_b128 v[142:145], v220 offset:2048
	ds_read_b128 v[146:149], v220 offset:4096
	ds_read_b128 v[150:153], v220 offset:6144
	ds_read_b128 v[154:157], v219
	ds_read_b128 v[158:161], v219 offset:2048
	ds_read_b128 v[162:165], v221
	ds_read_b128 v[166:169], v221 offset:2048
	ds_read_b128 v[170:173], v221 offset:4096
	ds_read_b128 v[174:177], v221 offset:6144
	s_add_u32 m0, s8, 0x0
	s_nop 0
	global_load_lds_dwordx4 v[202:203], off
	v_lshl_add_u64 v[202:203], v[202:203], 0, s[10:11]
	s_waitcnt lgkmcnt(9)
	v_mfma_f32_32x32x16_bf16 v[114:129], v[138:141], v[130:133], v[114:129]
	v_mfma_f32_32x32x16_bf16 v[98:113], v[138:141], v[134:137], v[98:113]
	s_add_u32 m0, s8, 0x400
	s_nop 0
	global_load_lds_dwordx4 v[204:205], off
	v_lshl_add_u64 v[204:205], v[204:205], 0, s[10:11]
	s_waitcnt lgkmcnt(8)
	v_mfma_f32_32x32x16_bf16 v[82:97], v[142:145], v[130:133], v[82:97]
	v_mfma_f32_32x32x16_bf16 v[66:81], v[142:145], v[134:137], v[66:81]
	s_add_u32 m0, s9, 0x0
	s_nop 0
	global_load_lds_dwordx4 v[206:207], off
	v_lshl_add_u64 v[206:207], v[206:207], 0, s[10:11]
	s_waitcnt lgkmcnt(7)
	v_mfma_f32_32x32x16_bf16 v[50:65], v[146:149], v[130:133], v[50:65]
	v_mfma_f32_32x32x16_bf16 v[34:49], v[146:149], v[134:137], v[34:49]
	s_add_u32 m0, s9, 0x400
	s_nop 0
	global_load_lds_dwordx4 v[208:209], off
	v_lshl_add_u64 v[208:209], v[208:209], 0, s[10:11]
	s_waitcnt lgkmcnt(6)
	v_mfma_f32_32x32x16_bf16 v[18:33], v[150:153], v[130:133], v[18:33]
	v_mfma_f32_32x32x16_bf16 v[2:17], v[150:153], v[134:137], v[2:17]
	s_add_u32 m0, s9, 0x800
	s_nop 0
	global_load_lds_dwordx4 v[210:211], off
	v_lshl_add_u64 v[210:211], v[210:211], 0, s[10:11]
	s_waitcnt lgkmcnt(3)
	v_mfma_f32_32x32x16_bf16 v[114:129], v[162:165], v[154:157], v[114:129]
	v_mfma_f32_32x32x16_bf16 v[98:113], v[162:165], v[158:161], v[98:113]
	s_add_u32 m0, s9, 0xc00
	s_nop 0
	global_load_lds_dwordx4 v[212:213], off
	v_lshl_add_u64 v[212:213], v[212:213], 0, s[10:11]
	s_waitcnt lgkmcnt(2)
	v_mfma_f32_32x32x16_bf16 v[82:97], v[166:169], v[154:157], v[82:97]
	v_mfma_f32_32x32x16_bf16 v[66:81], v[166:169], v[158:161], v[66:81]
	s_waitcnt lgkmcnt(1)
	v_mfma_f32_32x32x16_bf16 v[50:65], v[170:173], v[154:157], v[50:65]
	v_mfma_f32_32x32x16_bf16 v[34:49], v[170:173], v[158:161], v[34:49]
	s_waitcnt lgkmcnt(0)
	v_mfma_f32_32x32x16_bf16 v[18:33], v[174:177], v[154:157], v[18:33]
	v_mfma_f32_32x32x16_bf16 v[2:17], v[174:177], v[158:161], v[2:17]
	s_waitcnt vmcnt(6)
	s_barrier
	ds_read_b128 v[130:133], v222
	ds_read_b128 v[134:137], v222 offset:2048
	ds_read_b128 v[138:141], v224
	ds_read_b128 v[142:145], v224 offset:2048
	ds_read_b128 v[146:149], v224 offset:4096
	ds_read_b128 v[150:153], v224 offset:6144
	ds_read_b128 v[154:157], v223
	ds_read_b128 v[158:161], v223 offset:2048
	ds_read_b128 v[162:165], v225
	ds_read_b128 v[166:169], v225 offset:2048
	ds_read_b128 v[170:173], v225 offset:4096
	ds_read_b128 v[174:177], v225 offset:6144
	s_add_u32 m0, s8, 0x6000
	s_nop 0
	global_load_lds_dwordx4 v[202:203], off
	v_lshl_add_u64 v[202:203], v[202:203], 0, s[10:11]
	s_waitcnt lgkmcnt(9)
	v_mfma_f32_32x32x16_bf16 v[114:129], v[138:141], v[130:133], v[114:129]
	v_mfma_f32_32x32x16_bf16 v[98:113], v[138:141], v[134:137], v[98:113]
	s_add_u32 m0, s8, 0x6400
	s_nop 0
	global_load_lds_dwordx4 v[204:205], off
	v_lshl_add_u64 v[204:205], v[204:205], 0, s[10:11]
	s_waitcnt lgkmcnt(8)
	v_mfma_f32_32x32x16_bf16 v[82:97], v[142:145], v[130:133], v[82:97]
	v_mfma_f32_32x32x16_bf16 v[66:81], v[142:145], v[134:137], v[66:81]
	s_add_u32 m0, s9, 0x6000
	s_nop 0
	global_load_lds_dwordx4 v[206:207], off
	v_lshl_add_u64 v[206:207], v[206:207], 0, s[10:11]
	s_waitcnt lgkmcnt(7)
	v_mfma_f32_32x32x16_bf16 v[50:65], v[146:149], v[130:133], v[50:65]
	v_mfma_f32_32x32x16_bf16 v[34:49], v[146:149], v[134:137], v[34:49]
	s_add_u32 m0, s9, 0x6400
	s_nop 0
	global_load_lds_dwordx4 v[208:209], off
	v_lshl_add_u64 v[208:209], v[208:209], 0, s[10:11]
	s_waitcnt lgkmcnt(6)
	v_mfma_f32_32x32x16_bf16 v[18:33], v[150:153], v[130:133], v[18:33]
	v_mfma_f32_32x32x16_bf16 v[2:17], v[150:153], v[134:137], v[2:17]
	s_add_u32 m0, s9, 0x6800
	s_nop 0
	global_load_lds_dwordx4 v[210:211], off
	v_lshl_add_u64 v[210:211], v[210:211], 0, s[10:11]
	s_waitcnt lgkmcnt(3)
	v_mfma_f32_32x32x16_bf16 v[114:129], v[162:165], v[154:157], v[114:129]
	v_mfma_f32_32x32x16_bf16 v[98:113], v[162:165], v[158:161], v[98:113]
	s_add_u32 m0, s9, 0x6c00
	s_nop 0
	global_load_lds_dwordx4 v[212:213], off
	v_lshl_add_u64 v[212:213], v[212:213], 0, s[10:11]
	s_waitcnt lgkmcnt(2)
	v_mfma_f32_32x32x16_bf16 v[82:97], v[166:169], v[154:157], v[82:97]
	v_mfma_f32_32x32x16_bf16 v[66:81], v[166:169], v[158:161], v[66:81]
	s_waitcnt lgkmcnt(1)
	v_mfma_f32_32x32x16_bf16 v[50:65], v[170:173], v[154:157], v[50:65]
	v_mfma_f32_32x32x16_bf16 v[34:49], v[170:173], v[158:161], v[34:49]
	s_waitcnt lgkmcnt(0)
	v_mfma_f32_32x32x16_bf16 v[18:33], v[174:177], v[154:157], v[18:33]
	v_mfma_f32_32x32x16_bf16 v[2:17], v[174:177], v[158:161], v[2:17]
	s_sub_u32 s7, s7, 1
	s_cmp_lg_u32 s7, 0
	s_cbranch_scc1 .Lgemm_p7_loop
	s_waitcnt vmcnt(6)
	s_barrier
	ds_read_b128 v[130:133], v214
	ds_read_b128 v[134:137], v214 offset:2048
	ds_read_b128 v[138:141], v216
	ds_read_b128 v[142:145], v216 offset:2048
	ds_read_b128 v[146:149], v216 offset:4096
	ds_read_b128 v[150:153], v216 offset:6144
	ds_read_b128 v[154:157], v215
	ds_read_b128 v[158:161], v215 offset:2048
	ds_read_b128 v[162:165], v217
	ds_read_b128 v[166:169], v217 offset:2048
	ds_read_b128 v[170:173], v217 offset:4096
	ds_read_b128 v[174:177], v217 offset:6144
	s_waitcnt lgkmcnt(9)
	v_mfma_f32_32x32x16_bf16 v[114:129], v[138:141], v[130:133], v[114:129]
	v_mfma_f32_32x32x16_bf16 v[98:113], v[138:141], v[134:137], v[98:113]
	s_waitcnt lgkmcnt(8)
	v_mfma_f32_32x32x16_bf16 v[82:97], v[142:145], v[130:133], v[82:97]
	v_mfma_f32_32x32x16_bf16 v[66:81], v[142:145], v[134:137], v[66:81]
	s_waitcnt lgkmcnt(7)
	v_mfma_f32_32x32x16_bf16 v[50:65], v[146:149], v[130:133], v[50:65]
	v_mfma_f32_32x32x16_bf16 v[34:49], v[146:149], v[134:137], v[34:49]
	s_waitcnt lgkmcnt(6)
	v_mfma_f32_32x32x16_bf16 v[18:33], v[150:153], v[130:133], v[18:33]
	v_mfma_f32_32x32x16_bf16 v[2:17], v[150:153], v[134:137], v[2:17]
	s_waitcnt lgkmcnt(3)
	v_mfma_f32_32x32x16_bf16 v[114:129], v[162:165], v[154:157], v[114:129]
	v_mfma_f32_32x32x16_bf16 v[98:113], v[162:165], v[158:161], v[98:113]
	s_waitcnt lgkmcnt(2)
	v_mfma_f32_32x32x16_bf16 v[82:97], v[166:169], v[154:157], v[82:97]
	v_mfma_f32_32x32x16_bf16 v[66:81], v[166:169], v[158:161], v[66:81]
	s_waitcnt lgkmcnt(1)
	v_mfma_f32_32x32x16_bf16 v[50:65], v[170:173], v[154:157], v[50:65]
	v_mfma_f32_32x32x16_bf16 v[34:49], v[170:173], v[158:161], v[34:49]
	s_waitcnt lgkmcnt(0)
	v_mfma_f32_32x32x16_bf16 v[18:33], v[174:177], v[154:157], v[18:33]
	v_mfma_f32_32x32x16_bf16 v[2:17], v[174:177], v[158:161], v[2:17]
	s_waitcnt vmcnt(0)
	s_barrier
	ds_read_b128 v[130:133], v218
	ds_read_b128 v[134:137], v218 offset:2048
	ds_read_b128 v[138:141], v220
	ds_read_b128 v[142:145], v220 offset:2048
	ds_read_b128 v[146:149], v220 offset:4096
	ds_read_b128 v[150:153], v220 offset:6144
	ds_read_b128 v[154:157], v219
	ds_read_b128 v[158:161], v219 offset:2048
	ds_read_b128 v[162:165], v221
	ds_read_b128 v[166:169], v221 offset:2048
	ds_read_b128 v[170:173], v221 offset:4096
	ds_read_b128 v[174:177], v221 offset:6144
	s_waitcnt lgkmcnt(9)
	v_mfma_f32_32x32x16_bf16 v[114:129], v[138:141], v[130:133], v[114:129]
	v_mfma_f32_32x32x16_bf16 v[98:113], v[138:141], v[134:137], v[98:113]
	s_waitcnt lgkmcnt(8)
	v_mfma_f32_32x32x16_bf16 v[82:97], v[142:145], v[130:133], v[82:97]
	v_mfma_f32_32x32x16_bf16 v[66:81], v[142:145], v[134:137], v[66:81]
	s_waitcnt lgkmcnt(7)
	v_mfma_f32_32x32x16_bf16 v[50:65], v[146:149], v[130:133], v[50:65]
	v_mfma_f32_32x32x16_bf16 v[34:49], v[146:149], v[134:137], v[34:49]
	s_waitcnt lgkmcnt(6)
	v_mfma_f32_32x32x16_bf16 v[18:33], v[150:153], v[130:133], v[18:33]
	v_mfma_f32_32x32x16_bf16 v[2:17], v[150:153], v[134:137], v[2:17]
	s_waitcnt lgkmcnt(3)
	v_mfma_f32_32x32x16_bf16 v[114:129], v[162:165], v[154:157], v[114:129]
	v_mfma_f32_32x32x16_bf16 v[98:113], v[162:165], v[158:161], v[98:113]
	s_waitcnt lgkmcnt(2)
	v_mfma_f32_32x32x16_bf16 v[82:97], v[166:169], v[154:157], v[82:97]
	v_mfma_f32_32x32x16_bf16 v[66:81], v[166:169], v[158:161], v[66:81]
	s_waitcnt lgkmcnt(1)
	v_mfma_f32_32x32x16_bf16 v[50:65], v[170:173], v[154:157], v[50:65]
	v_mfma_f32_32x32x16_bf16 v[34:49], v[170:173], v[158:161], v[34:49]
	s_waitcnt lgkmcnt(0)
	v_mfma_f32_32x32x16_bf16 v[18:33], v[174:177], v[154:157], v[18:33]
	v_mfma_f32_32x32x16_bf16 v[2:17], v[174:177], v[158:161], v[2:17]
	s_movk_i32 s0, 0x2400
	v_mov_b32_e32 v131, v184
	s_nop 0
	v_ashrrev_i32_e32 v130, 1, v131
	v_ashrrev_i32_e32 v132, 6, v131
	v_and_b32_e32 v130, 0xffffffc0, v130
	v_lshlrev_b32_e32 v1, 7, v132
	v_add_u32_e32 v130, s22, v130
	v_mul_lo_u32 v133, v132, s0
	v_bfe_u32 v132, v131, 3, 3
	v_readlane_b32 s0, v247, 56
	v_readlane_b32 s1, v247, 57
	s_barrier
	v_and_b32_e32 v1, 0x80, v1
	v_or_b32_e32 v1, s23, v1
	v_lshrrev_b32_e32 v134, 3, v131
	v_and_b32_e32 v136, 4, v134
	v_lshlrev_b32_e32 v134, 1, v131
	v_lshlrev_b32_e32 v131, 4, v131
	v_and_or_b32 v137, v134, 62, v133
	v_and_b32_e32 v134, 0x70, v131
	v_ashrrev_i32_e32 v131, 31, v130
	v_lshl_add_u64 v[130:131], v[130:131], 1, s[0:1]
	v_mov_b32_e32 v135, v0
	s_movk_i32 s0, 0x90
	v_lshl_add_u64 v[130:131], v[130:131], 0, v[134:135]
	v_cvt_pk_bf16_f32 v114, v114, s0
	v_mad_u32_u24 v135, v136, s0, v137
	ds_write_b16 v135, v114
	v_cvt_pk_bf16_f32 v114, v115, s0
	ds_write_b16 v135, v114 offset:144
	v_cvt_pk_bf16_f32 v114, v116, s0
	v_or_b32_e32 v115, 3, v132
	ds_write_b16 v135, v114 offset:288
	v_cvt_pk_bf16_f32 v114, v117, s0
	v_mad_u32_u24 v115, v115, s0, v137
	ds_write_b16 v115, v114
	v_cvt_pk_bf16_f32 v114, v118, s0
	ds_write_b16 v135, v114 offset:1152
	v_cvt_pk_bf16_f32 v114, v119, s0
	ds_write_b16 v135, v114 offset:1296
	v_cvt_pk_bf16_f32 v114, v120, s0
	v_or_b32_e32 v116, 11, v132
	ds_write_b16 v135, v114 offset:1440
	v_cvt_pk_bf16_f32 v114, v121, s0
	v_mad_u32_u24 v116, v116, s0, v137
	ds_write_b16 v116, v114
	v_cvt_pk_bf16_f32 v114, v122, s0
	ds_write_b16 v135, v114 offset:2304
	v_cvt_pk_bf16_f32 v114, v123, s0
	ds_write_b16 v135, v114 offset:2448
	v_cvt_pk_bf16_f32 v114, v124, s0
	v_or_b32_e32 v117, 19, v132
	ds_write_b16 v135, v114 offset:2592
	v_cvt_pk_bf16_f32 v114, v125, s0
	v_mad_u32_u24 v117, v117, s0, v137
	ds_write_b16 v117, v114
	v_cvt_pk_bf16_f32 v114, v126, s0
	ds_write_b16 v135, v114 offset:3456
	v_cvt_pk_bf16_f32 v114, v127, s0
	ds_write_b16 v135, v114 offset:3600
	v_cvt_pk_bf16_f32 v114, v128, s0
	v_or_b32_e32 v118, 27, v132
	ds_write_b16 v135, v114 offset:3744
	v_cvt_pk_bf16_f32 v114, v129, s0
	v_mad_u32_u24 v118, v118, s0, v137
	v_cvt_pk_bf16_f32 v98, v98, s0
	ds_write_b16 v118, v114
	ds_write_b16 v135, v98 offset:64
	v_cvt_pk_bf16_f32 v98, v99, s0
	ds_write_b16 v135, v98 offset:208
	v_cvt_pk_bf16_f32 v98, v100, s0
	ds_write_b16 v135, v98 offset:352
	v_cvt_pk_bf16_f32 v98, v101, s0
	ds_write_b16 v115, v98 offset:64
	v_cvt_pk_bf16_f32 v98, v102, s0
	ds_write_b16 v135, v98 offset:1216
	v_cvt_pk_bf16_f32 v98, v103, s0
	ds_write_b16 v135, v98 offset:1360
	v_cvt_pk_bf16_f32 v98, v104, s0
	ds_write_b16 v135, v98 offset:1504
	v_cvt_pk_bf16_f32 v98, v105, s0
	ds_write_b16 v116, v98 offset:64
	v_cvt_pk_bf16_f32 v98, v106, s0
	ds_write_b16 v135, v98 offset:2368
	v_cvt_pk_bf16_f32 v98, v107, s0
	ds_write_b16 v135, v98 offset:2512
	v_cvt_pk_bf16_f32 v98, v108, s0
	ds_write_b16 v135, v98 offset:2656
	v_cvt_pk_bf16_f32 v98, v109, s0
	ds_write_b16 v117, v98 offset:64
	v_cvt_pk_bf16_f32 v98, v110, s0
	ds_write_b16 v135, v98 offset:3520
	v_cvt_pk_bf16_f32 v98, v111, s0
	ds_write_b16 v135, v98 offset:3664
	v_cvt_pk_bf16_f32 v98, v112, s0
	ds_write_b16 v135, v98 offset:3808
	v_cvt_pk_bf16_f32 v98, v113, s0
	v_cvt_pk_bf16_f32 v82, v82, s0
	ds_write_b16 v118, v98 offset:64
	ds_write_b16 v135, v82 offset:4608
	v_cvt_pk_bf16_f32 v82, v83, s0
	ds_write_b16 v135, v82 offset:4752
	v_cvt_pk_bf16_f32 v82, v84, s0
	v_or_b32_e32 v83, 35, v132
	ds_write_b16 v135, v82 offset:4896
	v_cvt_pk_bf16_f32 v82, v85, s0
	v_mad_u32_u24 v83, v83, s0, v137
	ds_write_b16 v83, v82
	v_cvt_pk_bf16_f32 v82, v86, s0
	ds_write_b16 v135, v82 offset:5760
	v_cvt_pk_bf16_f32 v82, v87, s0
	ds_write_b16 v135, v82 offset:5904
	v_cvt_pk_bf16_f32 v82, v88, s0
	v_or_b32_e32 v84, 43, v132
	ds_write_b16 v135, v82 offset:6048
	v_cvt_pk_bf16_f32 v82, v89, s0
	v_mad_u32_u24 v84, v84, s0, v137
	ds_write_b16 v84, v82
	v_cvt_pk_bf16_f32 v82, v90, s0
	ds_write_b16 v135, v82 offset:6912
	v_cvt_pk_bf16_f32 v82, v91, s0
	ds_write_b16 v135, v82 offset:7056
	v_cvt_pk_bf16_f32 v82, v92, s0
	v_or_b32_e32 v85, 51, v132
	ds_write_b16 v135, v82 offset:7200
	v_cvt_pk_bf16_f32 v82, v93, s0
	v_mad_u32_u24 v85, v85, s0, v137
	ds_write_b16 v85, v82
	v_cvt_pk_bf16_f32 v82, v94, s0
	ds_write_b16 v135, v82 offset:8064
	v_cvt_pk_bf16_f32 v82, v95, s0
	ds_write_b16 v135, v82 offset:8208
	v_cvt_pk_bf16_f32 v82, v96, s0
	v_or_b32_e32 v86, 59, v132
	ds_write_b16 v135, v82 offset:8352
	v_cvt_pk_bf16_f32 v82, v97, s0
	v_mad_u32_u24 v86, v86, s0, v137
	v_cvt_pk_bf16_f32 v66, v66, s0
	ds_write_b16 v86, v82
	ds_write_b16 v135, v66 offset:4672
	v_cvt_pk_bf16_f32 v66, v67, s0
	ds_write_b16 v135, v66 offset:4816
	v_cvt_pk_bf16_f32 v66, v68, s0
	ds_write_b16 v135, v66 offset:4960
	v_cvt_pk_bf16_f32 v66, v69, s0
	ds_write_b16 v83, v66 offset:64
	v_cvt_pk_bf16_f32 v66, v70, s0
	ds_write_b16 v135, v66 offset:5824
	v_cvt_pk_bf16_f32 v66, v71, s0
	ds_write_b16 v135, v66 offset:5968
	v_cvt_pk_bf16_f32 v66, v72, s0
	ds_write_b16 v135, v66 offset:6112
	v_cvt_pk_bf16_f32 v66, v73, s0
	ds_write_b16 v84, v66 offset:64
	v_cvt_pk_bf16_f32 v66, v74, s0
	ds_write_b16 v135, v66 offset:6976
	v_cvt_pk_bf16_f32 v66, v75, s0
	ds_write_b16 v135, v66 offset:7120
	v_cvt_pk_bf16_f32 v66, v76, s0
	ds_write_b16 v135, v66 offset:7264
	v_cvt_pk_bf16_f32 v66, v77, s0
	ds_write_b16 v85, v66 offset:64
	v_cvt_pk_bf16_f32 v66, v78, s0
	ds_write_b16 v135, v66 offset:8128
	v_cvt_pk_bf16_f32 v66, v79, s0
	v_or_b32_e32 v133, v133, v134
	ds_write_b16 v135, v66 offset:8272
	v_cvt_pk_bf16_f32 v66, v80, s0
	v_mad_u32_u24 v134, v132, s0, v133
	ds_write_b16 v135, v66 offset:8416
	v_cvt_pk_bf16_f32 v66, v81, s0
	ds_write_b16 v86, v66 offset:64
	s_waitcnt lgkmcnt(0)
	s_barrier
	ds_read_b128 v[66:69], v134
	v_or_b32_e32 v70, v1, v132
	v_mul_i32_i24_e32 v70, 0x14000, v70
	v_ashrrev_i32_e32 v71, 31, v70
	v_or_b32_e32 v72, 8, v132
	v_lshl_add_u64 v[70:71], v[130:131], 0, v[70:71]
	v_mad_u32_u24 v73, v72, s0, v133
	s_waitcnt lgkmcnt(0)
	global_store_dwordx4 v[70:71], v[66:69], off nt
	ds_read_b128 v[66:69], v73
	v_or_b32_e32 v70, v1, v72
	v_mul_i32_i24_e32 v70, 0x14000, v70
	v_ashrrev_i32_e32 v71, 31, v70
	v_lshl_add_u64 v[70:71], v[130:131], 0, v[70:71]
	s_waitcnt lgkmcnt(0)
	global_store_dwordx4 v[70:71], v[66:69], off nt
	v_or_b32_e32 v74, 16, v132
	ds_read_b128 v[66:69], v73 offset:1152
	v_or_b32_e32 v70, v1, v74
	v_mul_i32_i24_e32 v70, 0x14000, v70
	v_ashrrev_i32_e32 v71, 31, v70
	v_lshl_add_u64 v[70:71], v[130:131], 0, v[70:71]
	s_waitcnt lgkmcnt(0)
	global_store_dwordx4 v[70:71], v[66:69], off nt
	v_or_b32_e32 v75, 24, v132
	ds_read_b128 v[66:69], v73 offset:2304
	v_or_b32_e32 v70, v1, v75
	v_mul_i32_i24_e32 v70, 0x14000, v70
	v_ashrrev_i32_e32 v71, 31, v70
	v_lshl_add_u64 v[70:71], v[130:131], 0, v[70:71]
	s_waitcnt lgkmcnt(0)
	global_store_dwordx4 v[70:71], v[66:69], off nt
	v_or_b32_e32 v76, 32, v132
	ds_read_b128 v[66:69], v73 offset:3456
	v_or_b32_e32 v70, v1, v76
	v_mul_i32_i24_e32 v70, 0x14000, v70
	v_ashrrev_i32_e32 v71, 31, v70
	v_lshl_add_u64 v[70:71], v[130:131], 0, v[70:71]
	s_waitcnt lgkmcnt(0)
	global_store_dwordx4 v[70:71], v[66:69], off nt
	v_or_b32_e32 v77, 40, v132
	ds_read_b128 v[66:69], v73 offset:4608
	v_or_b32_e32 v70, v1, v77
	v_mul_i32_i24_e32 v70, 0x14000, v70
	v_ashrrev_i32_e32 v71, 31, v70
	v_lshl_add_u64 v[70:71], v[130:131], 0, v[70:71]
	s_waitcnt lgkmcnt(0)
	global_store_dwordx4 v[70:71], v[66:69], off nt
	v_or_b32_e32 v78, 48, v132
	ds_read_b128 v[66:69], v73 offset:5760
	v_or_b32_e32 v70, v1, v78
	v_mul_i32_i24_e32 v70, 0x14000, v70
	v_ashrrev_i32_e32 v71, 31, v70
	v_lshl_add_u64 v[70:71], v[130:131], 0, v[70:71]
	s_waitcnt lgkmcnt(0)
	global_store_dwordx4 v[70:71], v[66:69], off nt
	v_or_b32_e32 v79, 56, v132
	ds_read_b128 v[66:69], v73 offset:6912
	v_or_b32_e32 v70, v1, v79
	v_mul_i32_i24_e32 v70, 0x14000, v70
	v_ashrrev_i32_e32 v71, 31, v70
	v_lshl_add_u64 v[70:71], v[130:131], 0, v[70:71]
	v_cvt_pk_bf16_f32 v50, v50, s0
	s_waitcnt lgkmcnt(0)
	global_store_dwordx4 v[70:71], v[66:69], off nt
	s_barrier
	ds_write_b16 v135, v50
	v_cvt_pk_bf16_f32 v50, v51, s0
	ds_write_b16 v135, v50 offset:144
	v_cvt_pk_bf16_f32 v50, v52, s0
	ds_write_b16 v135, v50 offset:288
	v_cvt_pk_bf16_f32 v50, v53, s0
	ds_write_b16 v115, v50
	v_cvt_pk_bf16_f32 v50, v54, s0
	ds_write_b16 v135, v50 offset:1152
	v_cvt_pk_bf16_f32 v50, v55, s0
	ds_write_b16 v135, v50 offset:1296
	v_cvt_pk_bf16_f32 v50, v56, s0
	ds_write_b16 v135, v50 offset:1440
	v_cvt_pk_bf16_f32 v50, v57, s0
	ds_write_b16 v116, v50
	v_cvt_pk_bf16_f32 v50, v58, s0
	ds_write_b16 v135, v50 offset:2304
	v_cvt_pk_bf16_f32 v50, v59, s0
	ds_write_b16 v135, v50 offset:2448
	v_cvt_pk_bf16_f32 v50, v60, s0
	ds_write_b16 v135, v50 offset:2592
	v_cvt_pk_bf16_f32 v50, v61, s0
	ds_write_b16 v117, v50
	v_cvt_pk_bf16_f32 v50, v62, s0
	ds_write_b16 v135, v50 offset:3456
	v_cvt_pk_bf16_f32 v50, v63, s0
	ds_write_b16 v135, v50 offset:3600
	v_cvt_pk_bf16_f32 v50, v64, s0
	ds_write_b16 v135, v50 offset:3744
	v_cvt_pk_bf16_f32 v50, v65, s0
	v_cvt_pk_bf16_f32 v34, v34, s0
	ds_write_b16 v118, v50
	ds_write_b16 v135, v34 offset:64
	v_cvt_pk_bf16_f32 v34, v35, s0
	ds_write_b16 v135, v34 offset:208
	v_cvt_pk_bf16_f32 v34, v36, s0
	ds_write_b16 v135, v34 offset:352
	v_cvt_pk_bf16_f32 v34, v37, s0
	ds_write_b16 v115, v34 offset:64
	v_cvt_pk_bf16_f32 v34, v38, s0
	ds_write_b16 v135, v34 offset:1216
	v_cvt_pk_bf16_f32 v34, v39, s0
	ds_write_b16 v135, v34 offset:1360
	v_cvt_pk_bf16_f32 v34, v40, s0
	ds_write_b16 v135, v34 offset:1504
	v_cvt_pk_bf16_f32 v34, v41, s0
	ds_write_b16 v116, v34 offset:64
	v_cvt_pk_bf16_f32 v34, v42, s0
	ds_write_b16 v135, v34 offset:2368
	v_cvt_pk_bf16_f32 v34, v43, s0
	ds_write_b16 v135, v34 offset:2512
	v_cvt_pk_bf16_f32 v34, v44, s0
	ds_write_b16 v135, v34 offset:2656
	v_cvt_pk_bf16_f32 v34, v45, s0
	ds_write_b16 v117, v34 offset:64
	v_cvt_pk_bf16_f32 v34, v46, s0
	ds_write_b16 v135, v34 offset:3520
	v_cvt_pk_bf16_f32 v34, v47, s0
	ds_write_b16 v135, v34 offset:3664
	v_cvt_pk_bf16_f32 v34, v48, s0
	ds_write_b16 v135, v34 offset:3808
	v_cvt_pk_bf16_f32 v34, v49, s0
	v_cvt_pk_bf16_f32 v18, v18, s0
	ds_write_b16 v118, v34 offset:64
	ds_write_b16 v135, v18 offset:4608
	v_cvt_pk_bf16_f32 v18, v19, s0
	ds_write_b16 v135, v18 offset:4752
	v_cvt_pk_bf16_f32 v18, v20, s0
	ds_write_b16 v135, v18 offset:4896
	v_cvt_pk_bf16_f32 v18, v21, s0
	ds_write_b16 v83, v18
	v_cvt_pk_bf16_f32 v18, v22, s0
	ds_write_b16 v135, v18 offset:5760
	v_cvt_pk_bf16_f32 v18, v23, s0
	ds_write_b16 v135, v18 offset:5904
	v_cvt_pk_bf16_f32 v18, v24, s0
	ds_write_b16 v135, v18 offset:6048
	v_cvt_pk_bf16_f32 v18, v25, s0
	ds_write_b16 v84, v18
	v_cvt_pk_bf16_f32 v18, v26, s0
	ds_write_b16 v135, v18 offset:6912
	v_cvt_pk_bf16_f32 v18, v27, s0
	ds_write_b16 v135, v18 offset:7056
	v_cvt_pk_bf16_f32 v18, v28, s0
	ds_write_b16 v135, v18 offset:7200
	v_cvt_pk_bf16_f32 v18, v29, s0
	ds_write_b16 v85, v18
	v_cvt_pk_bf16_f32 v18, v30, s0
	ds_write_b16 v135, v18 offset:8064
	v_cvt_pk_bf16_f32 v18, v31, s0
	ds_write_b16 v135, v18 offset:8208
	v_cvt_pk_bf16_f32 v18, v32, s0
	ds_write_b16 v135, v18 offset:8352
	v_cvt_pk_bf16_f32 v18, v33, s0
	v_cvt_pk_bf16_f32 v2, v2, s0
	ds_write_b16 v86, v18
	ds_write_b16 v135, v2 offset:4672
	v_cvt_pk_bf16_f32 v2, v3, s0
	ds_write_b16 v135, v2 offset:4816
	v_cvt_pk_bf16_f32 v2, v4, s0
	ds_write_b16 v135, v2 offset:4960
	v_cvt_pk_bf16_f32 v2, v5, s0
	ds_write_b16 v83, v2 offset:64
	v_cvt_pk_bf16_f32 v2, v6, s0
	ds_write_b16 v135, v2 offset:5824
	v_cvt_pk_bf16_f32 v2, v7, s0
	ds_write_b16 v135, v2 offset:5968
	v_cvt_pk_bf16_f32 v2, v8, s0
	ds_write_b16 v135, v2 offset:6112
	v_cvt_pk_bf16_f32 v2, v9, s0
	ds_write_b16 v84, v2 offset:64
	v_cvt_pk_bf16_f32 v2, v10, s0
	ds_write_b16 v135, v2 offset:6976
	v_cvt_pk_bf16_f32 v2, v11, s0
	ds_write_b16 v135, v2 offset:7120
	v_cvt_pk_bf16_f32 v2, v12, s0
	ds_write_b16 v135, v2 offset:7264
	v_cvt_pk_bf16_f32 v2, v13, s0
	ds_write_b16 v85, v2 offset:64
	v_cvt_pk_bf16_f32 v2, v14, s0
	ds_write_b16 v135, v2 offset:8128
	v_cvt_pk_bf16_f32 v2, v15, s0
	ds_write_b16 v135, v2 offset:8272
	v_cvt_pk_bf16_f32 v2, v16, s0
	ds_write_b16 v135, v2 offset:8416
	v_cvt_pk_bf16_f32 v2, v17, s0
	ds_write_b16 v86, v2 offset:64
	s_waitcnt lgkmcnt(0)
	s_barrier
	ds_read_b128 v[2:5], v134
	v_or_b32_e32 v1, 64, v1
	v_or_b32_e32 v6, v1, v132
	v_mad_i64_i32 v[6:7], s[0:1], v6, s97, v[130:131]
	s_waitcnt lgkmcnt(0)
	global_store_dwordx4 v[6:7], v[2:5], off nt
	ds_read_b128 v[2:5], v73
	v_or_b32_e32 v6, v1, v72
	v_mad_i64_i32 v[6:7], s[0:1], v6, s97, v[130:131]
	s_waitcnt lgkmcnt(0)
	global_store_dwordx4 v[6:7], v[2:5], off nt
	ds_read_b128 v[2:5], v73 offset:1152
	v_or_b32_e32 v6, v1, v74
	v_mad_i64_i32 v[6:7], s[0:1], v6, s97, v[130:131]
	s_waitcnt lgkmcnt(0)
	global_store_dwordx4 v[6:7], v[2:5], off nt
	ds_read_b128 v[2:5], v73 offset:2304
	v_or_b32_e32 v6, v1, v75
	v_mad_i64_i32 v[6:7], s[0:1], v6, s97, v[130:131]
	s_waitcnt lgkmcnt(0)
	global_store_dwordx4 v[6:7], v[2:5], off nt
	ds_read_b128 v[2:5], v73 offset:3456
	v_or_b32_e32 v6, v1, v76
	v_mad_i64_i32 v[6:7], s[0:1], v6, s97, v[130:131]
	s_waitcnt lgkmcnt(0)
	global_store_dwordx4 v[6:7], v[2:5], off nt
	ds_read_b128 v[2:5], v73 offset:4608
	v_or_b32_e32 v6, v1, v77
	v_mad_i64_i32 v[6:7], s[0:1], v6, s97, v[130:131]
	s_waitcnt lgkmcnt(0)
	global_store_dwordx4 v[6:7], v[2:5], off nt
	ds_read_b128 v[2:5], v73 offset:5760
	v_or_b32_e32 v6, v1, v78
	v_mad_i64_i32 v[6:7], s[0:1], v6, s97, v[130:131]
	v_or_b32_e32 v1, v1, v79
	s_waitcnt lgkmcnt(0)
	global_store_dwordx4 v[6:7], v[2:5], off nt
	ds_read_b128 v[2:5], v73 offset:6912
	v_mad_i64_i32 v[6:7], s[0:1], v1, s97, v[130:131]
	v_readlane_b32 s0, v246, 1
	s_add_i32 s2, s2, s0
	s_cmpk_gt_i32 s2, 0x27f
	s_waitcnt lgkmcnt(0)
	global_store_dwordx4 v[6:7], v[2:5], off nt
	s_barrier
	s_cbranch_scc0 .LBB0_579

.LBB0_1098:
	s_movk_i32 s85, 0xff
	s_or_b64 exec, exec, s[0:1]
	v_ashrrev_i32_e32 v3, 31, v2
	s_cmpk_gt_u32 s47, 0x1ff
	v_lshl_add_u64 v[4:5], v[2:3], 2, s[68:69]
	s_waitcnt lgkmcnt(0)
	s_barrier
	s_cbranch_scc0 .LBB0_1102
	v_mov_b32_e32 v23, 0
	v_readlane_b32 s101, v245, 43
	s_nop 3
	s_lshr_b32 s101, s101, 3
	s_and_b32 s101, s101, 15
	s_lshl_b32 s22, s101, 7
	s_lshl_b32 s101, s101, 16
	s_mov_b32 s0, s101
	s_mov_b32 s1, 0
	v_mov_b32_e32 v22, v23
	v_mov_b32_e32 v47, v23
	v_mov_b32_e32 v46, v23
	v_mov_b32_e32 v63, v23
	v_mov_b32_e32 v62, v23
	v_mov_b32_e32 v97, v23
	v_mov_b32_e32 v96, v23
	v_mov_b32_e32 v8, v23
	v_mov_b32_e32 v9, v23
	v_mov_b32_e32 v6, v23
	v_mov_b32_e32 v7, v23
	v_mov_b32_e32 v10, v23
	v_mov_b32_e32 v11, v23
	v_mov_b32_e32 v14, v23
	v_mov_b32_e32 v15, v23
	v_mov_b32_e32 v32, v23
	v_mov_b32_e32 v33, v23
	v_mov_b32_e32 v34, v23
	v_mov_b32_e32 v35, v23
	v_mov_b32_e32 v40, v23
	v_mov_b32_e32 v41, v23
	v_mov_b32_e32 v42, v23
	v_mov_b32_e32 v43, v23
	v_mov_b32_e32 v48, v23
	v_mov_b32_e32 v49, v23
	v_mov_b32_e32 v50, v23
	v_mov_b32_e32 v51, v23
	v_mov_b32_e32 v54, v23
	v_mov_b32_e32 v55, v23
	v_mov_b32_e32 v16, v23
	v_mov_b32_e32 v17, v23
	v_mov_b32_e32 v56, v23
	v_mov_b32_e32 v57, v23
	v_mov_b32_e32 v76, v23
	v_mov_b32_e32 v77, v23
	v_mov_b32_e32 v82, v23
	v_mov_b32_e32 v83, v23
	v_mov_b32_e32 v86, v23
	v_mov_b32_e32 v87, v23
	v_mov_b32_e32 v90, v23
	v_mov_b32_e32 v91, v23
	v_mov_b32_e32 v92, v23
	v_mov_b32_e32 v93, v23
	v_mov_b32_e32 v94, v23
	v_mov_b32_e32 v95, v23
	v_mov_b32_e32 v98, v23
	v_mov_b32_e32 v99, v23
	v_mov_b32_e32 v78, v23
	v_mov_b32_e32 v79, v23
	v_mov_b32_e32 v100, v23
	v_mov_b32_e32 v101, v23
	v_mov_b32_e32 v102, v23
	v_mov_b32_e32 v103, v23
	v_mov_b32_e32 v114, v23
	v_mov_b32_e32 v115, v23
	v_mov_b32_e32 v116, v23
	v_mov_b32_e32 v117, v23
	v_mov_b32_e32 v126, v23
	v_mov_b32_e32 v127, v23
	v_mov_b32_e32 v128, v23
	v_mov_b32_e32 v129, v23
	v_mov_b32_e32 v132, v23
	v_mov_b32_e32 v133, v23
	v_mov_b32_e32 v130, v23
	v_mov_b32_e32 v131, v23
	v_mov_b32_e32 v104, v23
	v_mov_b32_e32 v105, v23
	v_mov_b32_e32 v58, v23
	v_mov_b32_e32 v59, v23
	v_mov_b32_e32 v12, v23
	v_mov_b32_e32 v13, v23
	v_mov_b32_e32 v18, v23
	v_mov_b32_e32 v19, v23
	v_mov_b32_e32 v24, v23
	v_mov_b32_e32 v25, v23
	v_mov_b32_e32 v26, v23
	v_mov_b32_e32 v27, v23
	v_mov_b32_e32 v28, v23
	v_mov_b32_e32 v29, v23
	v_mov_b32_e32 v30, v23
	v_mov_b32_e32 v31, v23
	v_mov_b32_e32 v36, v23
	v_mov_b32_e32 v37, v23
	v_mov_b32_e32 v38, v23
	v_mov_b32_e32 v39, v23
	v_mov_b32_e32 v44, v23
	v_mov_b32_e32 v45, v23
	v_mov_b32_e32 v20, v23
	v_mov_b32_e32 v21, v23
	v_mov_b32_e32 v52, v23
	v_mov_b32_e32 v53, v23
	v_mov_b32_e32 v64, v23
	v_mov_b32_e32 v65, v23
	v_mov_b32_e32 v68, v23
	v_mov_b32_e32 v69, v23
	v_mov_b32_e32 v70, v23
	v_mov_b32_e32 v71, v23
	v_mov_b32_e32 v72, v23
	v_mov_b32_e32 v73, v23
	v_mov_b32_e32 v74, v23
	v_mov_b32_e32 v75, v23
	v_mov_b32_e32 v80, v23
	v_mov_b32_e32 v81, v23
	v_mov_b32_e32 v84, v23
	v_mov_b32_e32 v85, v23
	v_mov_b32_e32 v66, v23
	v_mov_b32_e32 v67, v23
	v_mov_b32_e32 v88, v23
	v_mov_b32_e32 v89, v23
	v_mov_b32_e32 v106, v23
	v_mov_b32_e32 v107, v23
	v_mov_b32_e32 v110, v23
	v_mov_b32_e32 v111, v23
	v_mov_b32_e32 v112, v23
	v_mov_b32_e32 v113, v23
	v_mov_b32_e32 v118, v23
	v_mov_b32_e32 v119, v23
	v_mov_b32_e32 v120, v23
	v_mov_b32_e32 v121, v23
	v_mov_b32_e32 v124, v23
	v_mov_b32_e32 v125, v23
	v_mov_b32_e32 v122, v23
	v_mov_b32_e32 v123, v23
	v_mov_b32_e32 v108, v23
	v_mov_b32_e32 v109, v23
	v_mov_b32_e32 v60, v23
	v_mov_b32_e32 v61, v23
.LBB0_1100:
	v_lshl_add_u64 v[134:135], v[4:5], 0, s[0:1]
	s_mov_b32 s23, 0x1b46000
	v_add_co_u32_e32 v136, vcc, s23, v134
	s_mov_b32 s23, 0x1b47000
	s_nop 0
	v_addc_co_u32_e32 v137, vcc, 0, v135, vcc
	v_add_co_u32_e32 v138, vcc, s23, v134
	s_mov_b32 s23, 0x1b48000
	s_nop 0
	v_addc_co_u32_e32 v139, vcc, 0, v135, vcc
	global_load_dword v152, v[138:139], off offset:-4096
	global_load_dword v154, v[136:137], off offset:1024
	global_load_dword v156, v[136:137], off offset:2048
	global_load_dword v158, v[136:137], off offset:3072
	global_load_dword v160, v[138:139], off
	global_load_dword v162, v[138:139], off offset:1024
	global_load_dword v164, v[138:139], off offset:2048
	global_load_dword v166, v[138:139], off offset:3072
	v_add_co_u32_e32 v136, vcc, s23, v134
	s_mov_b32 s23, 0x1b49000
	s_nop 0
	v_addc_co_u32_e32 v137, vcc, 0, v135, vcc
	v_add_co_u32_e32 v138, vcc, s23, v134
	v_mov_b32_e32 v1, s22
	s_nop 0
	v_addc_co_u32_e32 v139, vcc, 0, v135, vcc
	global_load_dword v168, v[138:139], off offset:-4096
	global_load_dword v170, v[136:137], off offset:1024
	global_load_dword v172, v[136:137], off offset:2048
	global_load_dword v174, v[136:137], off offset:3072
	global_load_dword v176, v[138:139], off
	global_load_dword v180, v[138:139], off offset:1024
	global_load_dword v182, v[138:139], off offset:2048
	global_load_dword v202, v[138:139], off offset:3072
	ds_read_b128 v[136:139], v1
	ds_read_b128 v[140:143], v1 offset:16
	ds_read_b128 v[144:147], v1 offset:32
	ds_read_b128 v[148:151], v1 offset:48
	s_mov_b32 s23, 0x1b4a000
	s_add_u32 s0, s0, 0x10000
	s_addc_u32 s1, s1, 0
	s_addk_i32 s22, 0x80
	s_cmp_eq_u32 s0, 0x100000
	s_cselect_b32 s0, 0, s0
	s_cselect_b32 s22, 0, s22
	s_cmp_eq_u32 s0, s101
	s_waitcnt vmcnt(15) lgkmcnt(3)
	v_pk_fma_f32 v[132:133], v[152:153], v[136:137], v[132:133] op_sel_hi:[0,1,1]
	s_waitcnt vmcnt(14)
	v_pk_fma_f32 v[128:129], v[154:155], v[136:137], v[128:129] op_sel_hi:[0,1,1]
	s_waitcnt vmcnt(13)
	v_pk_fma_f32 v[116:117], v[156:157], v[136:137], v[116:117] op_sel_hi:[0,1,1]
	s_waitcnt vmcnt(12)
	v_pk_fma_f32 v[104:105], v[158:159], v[136:137], v[104:105] op_sel_hi:[0,1,1]
	s_waitcnt vmcnt(11)
	v_pk_fma_f32 v[100:101], v[160:161], v[136:137], v[100:101] op_sel_hi:[0,1,1]
	s_waitcnt vmcnt(10)
	v_pk_fma_f32 v[98:99], v[162:163], v[136:137], v[98:99] op_sel_hi:[0,1,1]
	s_waitcnt vmcnt(9)
	v_pk_fma_f32 v[92:93], v[164:165], v[136:137], v[92:93] op_sel_hi:[0,1,1]
	s_waitcnt vmcnt(8)
	v_pk_fma_f32 v[86:87], v[166:167], v[136:137], v[86:87] op_sel_hi:[0,1,1]
	v_pk_fma_f32 v[124:125], v[152:153], v[138:139], v[124:125] op_sel_hi:[0,1,1]
	v_pk_fma_f32 v[120:121], v[154:155], v[138:139], v[120:121] op_sel_hi:[0,1,1]
	v_pk_fma_f32 v[112:113], v[156:157], v[138:139], v[112:113] op_sel_hi:[0,1,1]
	s_waitcnt vmcnt(7)
	v_pk_fma_f32 v[76:77], v[168:169], v[136:137], v[76:77] op_sel_hi:[0,1,1]
	s_waitcnt vmcnt(6)
	v_pk_fma_f32 v[58:59], v[170:171], v[136:137], v[58:59] op_sel_hi:[0,1,1]
	s_waitcnt vmcnt(5)
	v_pk_fma_f32 v[46:47], v[172:173], v[136:137], v[46:47] op_sel_hi:[0,1,1]
	s_waitcnt vmcnt(4)
	v_pk_fma_f32 v[50:51], v[174:175], v[136:137], v[50:51] op_sel_hi:[0,1,1]
	s_waitcnt vmcnt(3)
	v_pk_fma_f32 v[42:43], v[176:177], v[136:137], v[42:43] op_sel_hi:[0,1,1]
	s_waitcnt vmcnt(2)
	v_pk_fma_f32 v[34:35], v[180:181], v[136:137], v[34:35] op_sel_hi:[0,1,1]
	s_waitcnt vmcnt(1)
	v_pk_fma_f32 v[16:17], v[182:183], v[136:137], v[16:17] op_sel_hi:[0,1,1]
	s_waitcnt vmcnt(0)
	v_pk_fma_f32 v[10:11], v[202:203], v[136:137], v[10:11] op_sel_hi:[0,1,1]
	v_add_co_u32_e32 v136, vcc, s23, v134
	s_mov_b32 s23, 0x1b4b000
	s_nop 0
	v_addc_co_u32_e32 v137, vcc, 0, v135, vcc
	v_pk_fma_f32 v[108:109], v[158:159], v[138:139], v[108:109] op_sel_hi:[0,1,1]
	v_pk_fma_f32 v[88:89], v[160:161], v[138:139], v[88:89] op_sel_hi:[0,1,1]
	v_pk_fma_f32 v[84:85], v[162:163], v[138:139], v[84:85] op_sel_hi:[0,1,1]
	v_pk_fma_f32 v[74:75], v[164:165], v[138:139], v[74:75] op_sel_hi:[0,1,1]
	v_pk_fma_f32 v[70:71], v[166:167], v[138:139], v[70:71] op_sel_hi:[0,1,1]
	v_pk_fma_f32 v[64:65], v[168:169], v[138:139], v[64:65] op_sel_hi:[0,1,1]
	v_pk_fma_f32 v[60:61], v[170:171], v[138:139], v[60:61] op_sel_hi:[0,1,1]
	v_pk_fma_f32 v[22:23], v[172:173], v[138:139], v[22:23] op_sel_hi:[0,1,1]
	v_pk_fma_f32 v[38:39], v[174:175], v[138:139], v[38:39] op_sel_hi:[0,1,1]
	v_pk_fma_f32 v[30:31], v[176:177], v[138:139], v[30:31] op_sel_hi:[0,1,1]
	v_pk_fma_f32 v[26:27], v[180:181], v[138:139], v[26:27] op_sel_hi:[0,1,1]
	v_pk_fma_f32 v[20:21], v[182:183], v[138:139], v[20:21] op_sel_hi:[0,1,1]
	v_pk_fma_f32 v[12:13], v[202:203], v[138:139], v[12:13] op_sel_hi:[0,1,1]
	v_add_co_u32_e32 v138, vcc, s23, v134
	s_mov_b32 s23, 0x1b4c000
	s_nop 0
	v_addc_co_u32_e32 v139, vcc, 0, v135, vcc
	s_waitcnt lgkmcnt(2)
	v_pk_fma_f32 v[96:97], v[160:161], v[140:141], v[96:97] op_sel_hi:[0,1,1]
	v_pk_fma_f32 v[62:63], v[160:161], v[142:143], v[62:63] op_sel_hi:[0,1,1]
	v_add_co_u32_e32 v160, vcc, s23, v134
	s_mov_b32 s23, 0x1b4d000
	s_nop 0
	v_addc_co_u32_e32 v161, vcc, 0, v135, vcc
	v_pk_fma_f32 v[94:95], v[162:163], v[140:141], v[94:95] op_sel_hi:[0,1,1]
	v_pk_fma_f32 v[80:81], v[162:163], v[142:143], v[80:81] op_sel_hi:[0,1,1]
	v_add_co_u32_e32 v162, vcc, s23, v134
	v_pk_fma_f32 v[130:131], v[152:153], v[140:141], v[130:131] op_sel_hi:[0,1,1]
	s_nop 0
	v_addc_co_u32_e32 v163, vcc, 0, v135, vcc
	v_pk_fma_f32 v[126:127], v[154:155], v[140:141], v[126:127] op_sel_hi:[0,1,1]
	v_pk_fma_f32 v[114:115], v[156:157], v[140:141], v[114:115] op_sel_hi:[0,1,1]
	v_pk_fma_f32 v[122:123], v[152:153], v[142:143], v[122:123] op_sel_hi:[0,1,1]
	v_pk_fma_f32 v[118:119], v[154:155], v[142:143], v[118:119] op_sel_hi:[0,1,1]
	v_pk_fma_f32 v[110:111], v[156:157], v[142:143], v[110:111] op_sel_hi:[0,1,1]
	v_pk_fma_f32 v[102:103], v[158:159], v[140:141], v[102:103] op_sel_hi:[0,1,1]
	v_pk_fma_f32 v[106:107], v[158:159], v[142:143], v[106:107] op_sel_hi:[0,1,1]
	v_pk_fma_f32 v[90:91], v[164:165], v[140:141], v[90:91] op_sel_hi:[0,1,1]
	v_pk_fma_f32 v[82:83], v[166:167], v[140:141], v[82:83] op_sel_hi:[0,1,1]
	v_pk_fma_f32 v[72:73], v[164:165], v[142:143], v[72:73] op_sel_hi:[0,1,1]
	v_pk_fma_f32 v[68:69], v[166:167], v[142:143], v[68:69] op_sel_hi:[0,1,1]
	v_pk_fma_f32 v[78:79], v[168:169], v[140:141], v[78:79] op_sel_hi:[0,1,1]
	v_pk_fma_f32 v[66:67], v[168:169], v[142:143], v[66:67] op_sel_hi:[0,1,1]
	v_pk_fma_f32 v[56:57], v[170:171], v[140:141], v[56:57] op_sel_hi:[0,1,1]
	v_pk_fma_f32 v[52:53], v[170:171], v[142:143], v[52:53] op_sel_hi:[0,1,1]
	v_pk_fma_f32 v[54:55], v[172:173], v[140:141], v[54:55] op_sel_hi:[0,1,1]
	v_pk_fma_f32 v[48:49], v[174:175], v[140:141], v[48:49] op_sel_hi:[0,1,1]
	v_pk_fma_f32 v[40:41], v[176:177], v[140:141], v[40:41] op_sel_hi:[0,1,1]
	v_pk_fma_f32 v[32:33], v[180:181], v[140:141], v[32:33] op_sel_hi:[0,1,1]
	v_pk_fma_f32 v[44:45], v[172:173], v[142:143], v[44:45] op_sel_hi:[0,1,1]
	v_pk_fma_f32 v[36:37], v[174:175], v[142:143], v[36:37] op_sel_hi:[0,1,1]
	v_pk_fma_f32 v[28:29], v[176:177], v[142:143], v[28:29] op_sel_hi:[0,1,1]
	v_pk_fma_f32 v[24:25], v[180:181], v[142:143], v[24:25] op_sel_hi:[0,1,1]
	v_pk_fma_f32 v[14:15], v[182:183], v[140:141], v[14:15] op_sel_hi:[0,1,1]
	v_pk_fma_f32 v[18:19], v[182:183], v[142:143], v[18:19] op_sel_hi:[0,1,1]
	v_pk_fma_f32 v[8:9], v[202:203], v[140:141], v[8:9] op_sel_hi:[0,1,1]
	v_pk_fma_f32 v[6:7], v[202:203], v[142:143], v[6:7] op_sel_hi:[0,1,1]
	global_load_dword v140, v[138:139], off offset:-4096
	global_load_dword v142, v[136:137], off offset:1024
	global_load_dword v152, v[136:137], off offset:2048
	s_nop 0
	global_load_dword v136, v[136:137], off offset:3072
	s_nop 0
	global_load_dword v154, v[138:139], off
	global_load_dword v156, v[138:139], off offset:1024
	global_load_dword v158, v[138:139], off offset:2048
	s_nop 0
	global_load_dword v138, v[138:139], off offset:3072
	s_nop 0
	global_load_dword v164, v[162:163], off offset:-4096
	global_load_dword v166, v[160:161], off offset:1024
	global_load_dword v168, v[160:161], off offset:2048
	s_nop 0
	global_load_dword v160, v[160:161], off offset:3072
	s_nop 0
	global_load_dword v170, v[162:163], off
	global_load_dword v172, v[162:163], off offset:1024
	global_load_dword v174, v[162:163], off offset:2048
	s_nop 0
	global_load_dword v162, v[162:163], off offset:3072
	s_mov_b32 s23, 0x1b4e000
	s_waitcnt vmcnt(15) lgkmcnt(1)
	v_pk_fma_f32 v[132:133], v[140:141], v[144:145], v[132:133] op_sel_hi:[0,1,1]
	s_waitcnt vmcnt(14)
	v_pk_fma_f32 v[128:129], v[142:143], v[144:145], v[128:129] op_sel_hi:[0,1,1]
	s_waitcnt lgkmcnt(0)
	v_pk_fma_f32 v[126:127], v[142:143], v[148:149], v[126:127] op_sel_hi:[0,1,1]
	v_pk_fma_f32 v[120:121], v[142:143], v[146:147], v[120:121] op_sel_hi:[0,1,1]
	v_pk_fma_f32 v[118:119], v[142:143], v[150:151], v[118:119] op_sel_hi:[0,1,1]
	v_pk_fma_f32 v[130:131], v[140:141], v[148:149], v[130:131] op_sel_hi:[0,1,1]
	v_pk_fma_f32 v[124:125], v[140:141], v[146:147], v[124:125] op_sel_hi:[0,1,1]
	v_pk_fma_f32 v[122:123], v[140:141], v[150:151], v[122:123] op_sel_hi:[0,1,1]
	s_waitcnt vmcnt(0)
	v_pk_fma_f32 v[142:143], v[162:163], v[150:151], v[6:7] op_sel_hi:[0,1,1]
	v_add_co_u32_e32 v6, vcc, s23, v134
	s_mov_b32 s23, 0x1b4f000
	s_nop 0
	v_addc_co_u32_e32 v7, vcc, 0, v135, vcc
	v_pk_fma_f32 v[140:141], v[162:163], v[148:149], v[8:9] op_sel_hi:[0,1,1]
	v_add_co_u32_e32 v8, vcc, s23, v134
	s_mov_b32 s23, 0x1b50000
	s_nop 0
	v_addc_co_u32_e32 v9, vcc, 0, v135, vcc
	v_pk_fma_f32 v[116:117], v[152:153], v[144:145], v[116:117] op_sel_hi:[0,1,1]
	v_pk_fma_f32 v[114:115], v[152:153], v[148:149], v[114:115] op_sel_hi:[0,1,1]
	v_pk_fma_f32 v[112:113], v[152:153], v[146:147], v[112:113] op_sel_hi:[0,1,1]
	v_pk_fma_f32 v[110:111], v[152:153], v[150:151], v[110:111] op_sel_hi:[0,1,1]
	v_pk_fma_f32 v[104:105], v[136:137], v[144:145], v[104:105] op_sel_hi:[0,1,1]
	v_pk_fma_f32 v[108:109], v[136:137], v[146:147], v[108:109] op_sel_hi:[0,1,1]
	v_pk_fma_f32 v[102:103], v[136:137], v[148:149], v[102:103] op_sel_hi:[0,1,1]
	v_pk_fma_f32 v[106:107], v[136:137], v[150:151], v[106:107] op_sel_hi:[0,1,1]
	v_pk_fma_f32 v[100:101], v[154:155], v[144:145], v[100:101] op_sel_hi:[0,1,1]
	v_pk_fma_f32 v[88:89], v[154:155], v[146:147], v[88:89] op_sel_hi:[0,1,1]
	v_pk_fma_f32 v[96:97], v[154:155], v[148:149], v[96:97] op_sel_hi:[0,1,1]
	v_pk_fma_f32 v[62:63], v[154:155], v[150:151], v[62:63] op_sel_hi:[0,1,1]
	v_pk_fma_f32 v[98:99], v[156:157], v[144:145], v[98:99] op_sel_hi:[0,1,1]
	v_pk_fma_f32 v[94:95], v[156:157], v[148:149], v[94:95] op_sel_hi:[0,1,1]
	v_pk_fma_f32 v[92:93], v[158:159], v[144:145], v[92:93] op_sel_hi:[0,1,1]
	v_pk_fma_f32 v[90:91], v[158:159], v[148:149], v[90:91] op_sel_hi:[0,1,1]
	v_pk_fma_f32 v[86:87], v[138:139], v[144:145], v[86:87] op_sel_hi:[0,1,1]
	v_pk_fma_f32 v[82:83], v[138:139], v[148:149], v[82:83] op_sel_hi:[0,1,1]
	v_pk_fma_f32 v[76:77], v[164:165], v[144:145], v[76:77] op_sel_hi:[0,1,1]
	v_pk_fma_f32 v[84:85], v[156:157], v[146:147], v[84:85] op_sel_hi:[0,1,1]
	v_pk_fma_f32 v[80:81], v[156:157], v[150:151], v[80:81] op_sel_hi:[0,1,1]
	v_pk_fma_f32 v[74:75], v[158:159], v[146:147], v[74:75] op_sel_hi:[0,1,1]
	v_pk_fma_f32 v[72:73], v[158:159], v[150:151], v[72:73] op_sel_hi:[0,1,1]
	v_pk_fma_f32 v[70:71], v[138:139], v[146:147], v[70:71] op_sel_hi:[0,1,1]
	v_pk_fma_f32 v[68:69], v[138:139], v[150:151], v[68:69] op_sel_hi:[0,1,1]
	v_pk_fma_f32 v[64:65], v[164:165], v[146:147], v[64:65] op_sel_hi:[0,1,1]
	v_pk_fma_f32 v[78:79], v[164:165], v[148:149], v[78:79] op_sel_hi:[0,1,1]
	v_pk_fma_f32 v[66:67], v[164:165], v[150:151], v[66:67] op_sel_hi:[0,1,1]
	v_pk_fma_f32 v[58:59], v[166:167], v[144:145], v[58:59] op_sel_hi:[0,1,1]
	v_pk_fma_f32 v[60:61], v[166:167], v[146:147], v[60:61] op_sel_hi:[0,1,1]
	v_pk_fma_f32 v[56:57], v[166:167], v[148:149], v[56:57] op_sel_hi:[0,1,1]
	v_pk_fma_f32 v[52:53], v[166:167], v[150:151], v[52:53] op_sel_hi:[0,1,1]
	v_pk_fma_f32 v[46:47], v[168:169], v[144:145], v[46:47] op_sel_hi:[0,1,1]
	v_pk_fma_f32 v[22:23], v[168:169], v[146:147], v[22:23] op_sel_hi:[0,1,1]
	v_pk_fma_f32 v[54:55], v[168:169], v[148:149], v[54:55] op_sel_hi:[0,1,1]
	v_pk_fma_f32 v[50:51], v[160:161], v[144:145], v[50:51] op_sel_hi:[0,1,1]
	v_pk_fma_f32 v[48:49], v[160:161], v[148:149], v[48:49] op_sel_hi:[0,1,1]
	v_pk_fma_f32 v[42:43], v[170:171], v[144:145], v[42:43] op_sel_hi:[0,1,1]
	v_pk_fma_f32 v[40:41], v[170:171], v[148:149], v[40:41] op_sel_hi:[0,1,1]
	v_pk_fma_f32 v[34:35], v[172:173], v[144:145], v[34:35] op_sel_hi:[0,1,1]
	v_pk_fma_f32 v[32:33], v[172:173], v[148:149], v[32:33] op_sel_hi:[0,1,1]
	v_pk_fma_f32 v[44:45], v[168:169], v[150:151], v[44:45] op_sel_hi:[0,1,1]
	v_pk_fma_f32 v[38:39], v[160:161], v[146:147], v[38:39] op_sel_hi:[0,1,1]
	v_pk_fma_f32 v[36:37], v[160:161], v[150:151], v[36:37] op_sel_hi:[0,1,1]
	v_pk_fma_f32 v[30:31], v[170:171], v[146:147], v[30:31] op_sel_hi:[0,1,1]
	v_pk_fma_f32 v[28:29], v[170:171], v[150:151], v[28:29] op_sel_hi:[0,1,1]
	v_pk_fma_f32 v[26:27], v[172:173], v[146:147], v[26:27] op_sel_hi:[0,1,1]
	v_pk_fma_f32 v[24:25], v[172:173], v[150:151], v[24:25] op_sel_hi:[0,1,1]
	v_pk_fma_f32 v[16:17], v[174:175], v[144:145], v[16:17] op_sel_hi:[0,1,1]
	v_pk_fma_f32 v[20:21], v[174:175], v[146:147], v[20:21] op_sel_hi:[0,1,1]
	v_pk_fma_f32 v[14:15], v[174:175], v[148:149], v[14:15] op_sel_hi:[0,1,1]
	v_pk_fma_f32 v[18:19], v[174:175], v[150:151], v[18:19] op_sel_hi:[0,1,1]
	v_pk_fma_f32 v[136:137], v[162:163], v[144:145], v[10:11] op_sel_hi:[0,1,1]
	v_pk_fma_f32 v[138:139], v[162:163], v[146:147], v[12:13] op_sel_hi:[0,1,1]
	global_load_dword v144, v[8:9], off offset:-4096
	global_load_dword v146, v[6:7], off offset:1024
	global_load_dword v148, v[6:7], off offset:2048
	global_load_dword v150, v[6:7], off offset:3072
	global_load_dword v152, v[8:9], off
	global_load_dword v154, v[8:9], off offset:1024
	global_load_dword v156, v[8:9], off offset:2048
	global_load_dword v158, v[8:9], off offset:3072
	v_add_co_u32_e32 v6, vcc, s23, v134
	s_mov_b32 s23, 0x1b51000
	s_nop 0
	v_addc_co_u32_e32 v7, vcc, 0, v135, vcc
	v_add_co_u32_e32 v8, vcc, s23, v134
	s_mov_b32 s23, 0x1b52000
	s_nop 0
	v_addc_co_u32_e32 v9, vcc, 0, v135, vcc
	global_load_dword v160, v[8:9], off offset:-4096
	global_load_dword v162, v[6:7], off offset:1024
	global_load_dword v164, v[6:7], off offset:2048
	global_load_dword v166, v[6:7], off offset:3072
	global_load_dword v168, v[8:9], off
	global_load_dword v170, v[8:9], off offset:1024
	global_load_dword v172, v[8:9], off offset:2048
	global_load_dword v174, v[8:9], off offset:3072
	ds_read_b128 v[6:9], v1 offset:64
	ds_read_b128 v[10:13], v1 offset:80
	s_waitcnt vmcnt(15) lgkmcnt(1)
	v_pk_fma_f32 v[132:133], v[144:145], v[6:7], v[132:133] op_sel_hi:[0,1,1]
	s_waitcnt lgkmcnt(0)
	v_pk_fma_f32 v[130:131], v[144:145], v[10:11], v[130:131] op_sel_hi:[0,1,1]
	s_waitcnt vmcnt(14)
	v_pk_fma_f32 v[128:129], v[146:147], v[6:7], v[128:129] op_sel_hi:[0,1,1]
	s_waitcnt vmcnt(13)
	v_pk_fma_f32 v[116:117], v[148:149], v[6:7], v[116:117] op_sel_hi:[0,1,1]
	v_pk_fma_f32 v[124:125], v[144:145], v[8:9], v[124:125] op_sel_hi:[0,1,1]
	v_pk_fma_f32 v[122:123], v[144:145], v[12:13], v[122:123] op_sel_hi:[0,1,1]
	s_waitcnt vmcnt(12)
	v_pk_fma_f32 v[104:105], v[150:151], v[6:7], v[104:105] op_sel_hi:[0,1,1]
	s_waitcnt vmcnt(11)
	v_pk_fma_f32 v[100:101], v[152:153], v[6:7], v[100:101] op_sel_hi:[0,1,1]
	s_waitcnt vmcnt(10)
	v_pk_fma_f32 v[98:99], v[154:155], v[6:7], v[98:99] op_sel_hi:[0,1,1]
	s_waitcnt vmcnt(9)
	v_pk_fma_f32 v[92:93], v[156:157], v[6:7], v[92:93] op_sel_hi:[0,1,1]
	s_waitcnt vmcnt(8)
	v_pk_fma_f32 v[86:87], v[158:159], v[6:7], v[86:87] op_sel_hi:[0,1,1]
	s_waitcnt vmcnt(7)
	v_pk_fma_f32 v[76:77], v[160:161], v[6:7], v[76:77] op_sel_hi:[0,1,1]
	s_waitcnt vmcnt(6)
	v_pk_fma_f32 v[58:59], v[162:163], v[6:7], v[58:59] op_sel_hi:[0,1,1]
	s_waitcnt vmcnt(5)
	v_pk_fma_f32 v[46:47], v[164:165], v[6:7], v[46:47] op_sel_hi:[0,1,1]
	s_waitcnt vmcnt(4)
	v_pk_fma_f32 v[50:51], v[166:167], v[6:7], v[50:51] op_sel_hi:[0,1,1]
	s_waitcnt vmcnt(3)
	v_pk_fma_f32 v[42:43], v[168:169], v[6:7], v[42:43] op_sel_hi:[0,1,1]
	s_waitcnt vmcnt(2)
	v_pk_fma_f32 v[34:35], v[170:171], v[6:7], v[34:35] op_sel_hi:[0,1,1]
	s_waitcnt vmcnt(1)
	v_pk_fma_f32 v[16:17], v[172:173], v[6:7], v[16:17] op_sel_hi:[0,1,1]
	s_waitcnt vmcnt(0)
	v_pk_fma_f32 v[144:145], v[174:175], v[6:7], v[136:137] op_sel_hi:[0,1,1]
	v_add_co_u32_e32 v6, vcc, s23, v134
	s_mov_b32 s23, 0x1b53000
	s_nop 0
	v_addc_co_u32_e32 v7, vcc, 0, v135, vcc
	v_pk_fma_f32 v[120:121], v[146:147], v[8:9], v[120:121] op_sel_hi:[0,1,1]
	v_pk_fma_f32 v[112:113], v[148:149], v[8:9], v[112:113] op_sel_hi:[0,1,1]
	v_pk_fma_f32 v[108:109], v[150:151], v[8:9], v[108:109] op_sel_hi:[0,1,1]
	v_pk_fma_f32 v[88:89], v[152:153], v[8:9], v[88:89] op_sel_hi:[0,1,1]
	v_pk_fma_f32 v[84:85], v[154:155], v[8:9], v[84:85] op_sel_hi:[0,1,1]
	v_pk_fma_f32 v[74:75], v[156:157], v[8:9], v[74:75] op_sel_hi:[0,1,1]
	v_pk_fma_f32 v[70:71], v[158:159], v[8:9], v[70:71] op_sel_hi:[0,1,1]
	v_pk_fma_f32 v[64:65], v[160:161], v[8:9], v[64:65] op_sel_hi:[0,1,1]
	v_pk_fma_f32 v[60:61], v[162:163], v[8:9], v[60:61] op_sel_hi:[0,1,1]
	v_pk_fma_f32 v[22:23], v[164:165], v[8:9], v[22:23] op_sel_hi:[0,1,1]
	v_pk_fma_f32 v[38:39], v[166:167], v[8:9], v[38:39] op_sel_hi:[0,1,1]
	v_pk_fma_f32 v[30:31], v[168:169], v[8:9], v[30:31] op_sel_hi:[0,1,1]
	v_pk_fma_f32 v[26:27], v[170:171], v[8:9], v[26:27] op_sel_hi:[0,1,1]
	v_pk_fma_f32 v[20:21], v[172:173], v[8:9], v[20:21] op_sel_hi:[0,1,1]
	v_pk_fma_f32 v[138:139], v[174:175], v[8:9], v[138:139] op_sel_hi:[0,1,1]
	v_add_co_u32_e32 v8, vcc, s23, v134
	s_mov_b32 s23, 0x1b54000
	s_nop 0
	v_addc_co_u32_e32 v9, vcc, 0, v135, vcc
	v_pk_fma_f32 v[126:127], v[146:147], v[10:11], v[126:127] op_sel_hi:[0,1,1]
	v_pk_fma_f32 v[114:115], v[148:149], v[10:11], v[114:115] op_sel_hi:[0,1,1]
	v_pk_fma_f32 v[118:119], v[146:147], v[12:13], v[118:119] op_sel_hi:[0,1,1]
	v_pk_fma_f32 v[110:111], v[148:149], v[12:13], v[110:111] op_sel_hi:[0,1,1]
	v_pk_fma_f32 v[102:103], v[150:151], v[10:11], v[102:103] op_sel_hi:[0,1,1]
	v_pk_fma_f32 v[106:107], v[150:151], v[12:13], v[106:107] op_sel_hi:[0,1,1]
	v_pk_fma_f32 v[96:97], v[152:153], v[10:11], v[96:97] op_sel_hi:[0,1,1]
	v_pk_fma_f32 v[62:63], v[152:153], v[12:13], v[62:63] op_sel_hi:[0,1,1]
	v_pk_fma_f32 v[94:95], v[154:155], v[10:11], v[94:95] op_sel_hi:[0,1,1]
	v_pk_fma_f32 v[90:91], v[156:157], v[10:11], v[90:91] op_sel_hi:[0,1,1]
	v_pk_fma_f32 v[82:83], v[158:159], v[10:11], v[82:83] op_sel_hi:[0,1,1]
	v_pk_fma_f32 v[80:81], v[154:155], v[12:13], v[80:81] op_sel_hi:[0,1,1]
	v_pk_fma_f32 v[72:73], v[156:157], v[12:13], v[72:73] op_sel_hi:[0,1,1]
	v_pk_fma_f32 v[68:69], v[158:159], v[12:13], v[68:69] op_sel_hi:[0,1,1]
	v_pk_fma_f32 v[78:79], v[160:161], v[10:11], v[78:79] op_sel_hi:[0,1,1]
	v_pk_fma_f32 v[66:67], v[160:161], v[12:13], v[66:67] op_sel_hi:[0,1,1]
	v_pk_fma_f32 v[56:57], v[162:163], v[10:11], v[56:57] op_sel_hi:[0,1,1]
	v_pk_fma_f32 v[52:53], v[162:163], v[12:13], v[52:53] op_sel_hi:[0,1,1]
	v_pk_fma_f32 v[54:55], v[164:165], v[10:11], v[54:55] op_sel_hi:[0,1,1]
	v_pk_fma_f32 v[48:49], v[166:167], v[10:11], v[48:49] op_sel_hi:[0,1,1]
	v_pk_fma_f32 v[40:41], v[168:169], v[10:11], v[40:41] op_sel_hi:[0,1,1]
	v_pk_fma_f32 v[32:33], v[170:171], v[10:11], v[32:33] op_sel_hi:[0,1,1]
	v_pk_fma_f32 v[44:45], v[164:165], v[12:13], v[44:45] op_sel_hi:[0,1,1]
	v_pk_fma_f32 v[36:37], v[166:167], v[12:13], v[36:37] op_sel_hi:[0,1,1]
	v_pk_fma_f32 v[28:29], v[168:169], v[12:13], v[28:29] op_sel_hi:[0,1,1]
	v_pk_fma_f32 v[24:25], v[170:171], v[12:13], v[24:25] op_sel_hi:[0,1,1]
	v_pk_fma_f32 v[14:15], v[172:173], v[10:11], v[14:15] op_sel_hi:[0,1,1]
	v_pk_fma_f32 v[18:19], v[172:173], v[12:13], v[18:19] op_sel_hi:[0,1,1]
	v_pk_fma_f32 v[140:141], v[174:175], v[10:11], v[140:141] op_sel_hi:[0,1,1]
	v_pk_fma_f32 v[142:143], v[174:175], v[12:13], v[142:143] op_sel_hi:[0,1,1]
	global_load_dword v10, v[8:9], off offset:-4096
	global_load_dword v12, v[6:7], off offset:1024
	global_load_dword v146, v[6:7], off offset:2048
	global_load_dword v148, v[6:7], off offset:3072
	global_load_dword v150, v[8:9], off
	global_load_dword v152, v[8:9], off offset:1024
	global_load_dword v154, v[8:9], off offset:2048
	global_load_dword v156, v[8:9], off offset:3072
	v_add_co_u32_e32 v6, vcc, s23, v134
	s_mov_b32 s23, 0x1b55000
	s_nop 0
	v_addc_co_u32_e32 v7, vcc, 0, v135, vcc
	v_add_co_u32_e32 v8, vcc, s23, v134
	s_nop 1
	v_addc_co_u32_e32 v9, vcc, 0, v135, vcc
	global_load_dword v158, v[8:9], off offset:-4096
	global_load_dword v160, v[6:7], off offset:1024
	global_load_dword v162, v[6:7], off offset:2048
	global_load_dword v164, v[6:7], off offset:3072
	global_load_dword v166, v[8:9], off
	global_load_dword v168, v[8:9], off offset:1024
	global_load_dword v170, v[8:9], off offset:2048
	global_load_dword v172, v[8:9], off offset:3072
	ds_read_b128 v[6:9], v1 offset:96
	ds_read_b128 v[134:137], v1 offset:112
	s_waitcnt vmcnt(15) lgkmcnt(1)
	v_pk_fma_f32 v[132:133], v[10:11], v[6:7], v[132:133] op_sel_hi:[0,1,1]
	s_waitcnt lgkmcnt(0)
	v_pk_fma_f32 v[130:131], v[10:11], v[134:135], v[130:131] op_sel_hi:[0,1,1]
	s_waitcnt vmcnt(14)
	v_pk_fma_f32 v[128:129], v[12:13], v[6:7], v[128:129] op_sel_hi:[0,1,1]
	v_pk_fma_f32 v[126:127], v[12:13], v[134:135], v[126:127] op_sel_hi:[0,1,1]
	s_waitcnt vmcnt(13)
	v_pk_fma_f32 v[116:117], v[146:147], v[6:7], v[116:117] op_sel_hi:[0,1,1]
	v_pk_fma_f32 v[114:115], v[146:147], v[134:135], v[114:115] op_sel_hi:[0,1,1]
	v_pk_fma_f32 v[124:125], v[10:11], v[8:9], v[124:125] op_sel_hi:[0,1,1]
	v_pk_fma_f32 v[122:123], v[10:11], v[136:137], v[122:123] op_sel_hi:[0,1,1]
	v_pk_fma_f32 v[120:121], v[12:13], v[8:9], v[120:121] op_sel_hi:[0,1,1]
	v_pk_fma_f32 v[118:119], v[12:13], v[136:137], v[118:119] op_sel_hi:[0,1,1]
	v_pk_fma_f32 v[112:113], v[146:147], v[8:9], v[112:113] op_sel_hi:[0,1,1]
	v_pk_fma_f32 v[110:111], v[146:147], v[136:137], v[110:111] op_sel_hi:[0,1,1]
	s_waitcnt vmcnt(12)
	v_pk_fma_f32 v[104:105], v[148:149], v[6:7], v[104:105] op_sel_hi:[0,1,1]
	v_pk_fma_f32 v[108:109], v[148:149], v[8:9], v[108:109] op_sel_hi:[0,1,1]
	v_pk_fma_f32 v[102:103], v[148:149], v[134:135], v[102:103] op_sel_hi:[0,1,1]
	v_pk_fma_f32 v[106:107], v[148:149], v[136:137], v[106:107] op_sel_hi:[0,1,1]
	s_waitcnt vmcnt(11)
	v_pk_fma_f32 v[100:101], v[150:151], v[6:7], v[100:101] op_sel_hi:[0,1,1]
	v_pk_fma_f32 v[88:89], v[150:151], v[8:9], v[88:89] op_sel_hi:[0,1,1]
	v_pk_fma_f32 v[96:97], v[150:151], v[134:135], v[96:97] op_sel_hi:[0,1,1]
	v_pk_fma_f32 v[62:63], v[150:151], v[136:137], v[62:63] op_sel_hi:[0,1,1]
	s_waitcnt vmcnt(10)
	v_pk_fma_f32 v[98:99], v[152:153], v[6:7], v[98:99] op_sel_hi:[0,1,1]
	v_pk_fma_f32 v[94:95], v[152:153], v[134:135], v[94:95] op_sel_hi:[0,1,1]
	s_waitcnt vmcnt(9)
	v_pk_fma_f32 v[92:93], v[154:155], v[6:7], v[92:93] op_sel_hi:[0,1,1]
	v_pk_fma_f32 v[90:91], v[154:155], v[134:135], v[90:91] op_sel_hi:[0,1,1]
	s_waitcnt vmcnt(8)
	v_pk_fma_f32 v[86:87], v[156:157], v[6:7], v[86:87] op_sel_hi:[0,1,1]
	v_pk_fma_f32 v[82:83], v[156:157], v[134:135], v[82:83] op_sel_hi:[0,1,1]
	s_waitcnt vmcnt(7)
	v_pk_fma_f32 v[76:77], v[158:159], v[6:7], v[76:77] op_sel_hi:[0,1,1]
	v_pk_fma_f32 v[84:85], v[152:153], v[8:9], v[84:85] op_sel_hi:[0,1,1]
	v_pk_fma_f32 v[80:81], v[152:153], v[136:137], v[80:81] op_sel_hi:[0,1,1]
	v_pk_fma_f32 v[74:75], v[154:155], v[8:9], v[74:75] op_sel_hi:[0,1,1]
	v_pk_fma_f32 v[72:73], v[154:155], v[136:137], v[72:73] op_sel_hi:[0,1,1]
	v_pk_fma_f32 v[70:71], v[156:157], v[8:9], v[70:71] op_sel_hi:[0,1,1]
	v_pk_fma_f32 v[68:69], v[156:157], v[136:137], v[68:69] op_sel_hi:[0,1,1]
	v_pk_fma_f32 v[64:65], v[158:159], v[8:9], v[64:65] op_sel_hi:[0,1,1]
	v_pk_fma_f32 v[78:79], v[158:159], v[134:135], v[78:79] op_sel_hi:[0,1,1]
	v_pk_fma_f32 v[66:67], v[158:159], v[136:137], v[66:67] op_sel_hi:[0,1,1]
	s_waitcnt vmcnt(6)
	v_pk_fma_f32 v[58:59], v[160:161], v[6:7], v[58:59] op_sel_hi:[0,1,1]
	v_pk_fma_f32 v[60:61], v[160:161], v[8:9], v[60:61] op_sel_hi:[0,1,1]
	v_pk_fma_f32 v[56:57], v[160:161], v[134:135], v[56:57] op_sel_hi:[0,1,1]
	v_pk_fma_f32 v[52:53], v[160:161], v[136:137], v[52:53] op_sel_hi:[0,1,1]
	s_waitcnt vmcnt(5)
	v_pk_fma_f32 v[46:47], v[162:163], v[6:7], v[46:47] op_sel_hi:[0,1,1]
	v_pk_fma_f32 v[22:23], v[162:163], v[8:9], v[22:23] op_sel_hi:[0,1,1]
	v_pk_fma_f32 v[54:55], v[162:163], v[134:135], v[54:55] op_sel_hi:[0,1,1]
	s_waitcnt vmcnt(4)
	v_pk_fma_f32 v[50:51], v[164:165], v[6:7], v[50:51] op_sel_hi:[0,1,1]
	v_pk_fma_f32 v[48:49], v[164:165], v[134:135], v[48:49] op_sel_hi:[0,1,1]
	s_waitcnt vmcnt(3)
	v_pk_fma_f32 v[42:43], v[166:167], v[6:7], v[42:43] op_sel_hi:[0,1,1]
	v_pk_fma_f32 v[40:41], v[166:167], v[134:135], v[40:41] op_sel_hi:[0,1,1]
	s_waitcnt vmcnt(2)
	v_pk_fma_f32 v[34:35], v[168:169], v[6:7], v[34:35] op_sel_hi:[0,1,1]
	v_pk_fma_f32 v[32:33], v[168:169], v[134:135], v[32:33] op_sel_hi:[0,1,1]
	v_pk_fma_f32 v[44:45], v[162:163], v[136:137], v[44:45] op_sel_hi:[0,1,1]
	v_pk_fma_f32 v[38:39], v[164:165], v[8:9], v[38:39] op_sel_hi:[0,1,1]
	v_pk_fma_f32 v[36:37], v[164:165], v[136:137], v[36:37] op_sel_hi:[0,1,1]
	v_pk_fma_f32 v[30:31], v[166:167], v[8:9], v[30:31] op_sel_hi:[0,1,1]
	v_pk_fma_f32 v[28:29], v[166:167], v[136:137], v[28:29] op_sel_hi:[0,1,1]
	v_pk_fma_f32 v[26:27], v[168:169], v[8:9], v[26:27] op_sel_hi:[0,1,1]
	v_pk_fma_f32 v[24:25], v[168:169], v[136:137], v[24:25] op_sel_hi:[0,1,1]
	s_waitcnt vmcnt(1)
	v_pk_fma_f32 v[16:17], v[170:171], v[6:7], v[16:17] op_sel_hi:[0,1,1]
	v_pk_fma_f32 v[20:21], v[170:171], v[8:9], v[20:21] op_sel_hi:[0,1,1]
	v_pk_fma_f32 v[14:15], v[170:171], v[134:135], v[14:15] op_sel_hi:[0,1,1]
	v_pk_fma_f32 v[18:19], v[170:171], v[136:137], v[18:19] op_sel_hi:[0,1,1]
	s_waitcnt vmcnt(0)
	v_pk_fma_f32 v[10:11], v[172:173], v[6:7], v[144:145] op_sel_hi:[0,1,1]
	v_pk_fma_f32 v[12:13], v[172:173], v[8:9], v[138:139] op_sel_hi:[0,1,1]
	v_pk_fma_f32 v[8:9], v[172:173], v[134:135], v[140:141] op_sel_hi:[0,1,1]
	v_pk_fma_f32 v[6:7], v[172:173], v[136:137], v[142:143] op_sel_hi:[0,1,1]
	s_cbranch_scc0 .LBB0_1100
	v_cvt_f32_i32_e32 v1, v2
	s_mov_b32 s6, 0x457ff000
	v_add_u32_e32 v146, 0x100, v2
	s_or_b32 s22, s46, 2
	v_div_scale_f32 v136, s[0:1], s6, s6, v1
	v_rcp_f32_e32 v137, v136
	v_div_scale_f32 v139, vcc, v1, s6, v1
	v_cvt_f32_u32_e32 v138, s46
	v_fma_f32 v140, -v136, v137, 1.0
	v_fmac_f32_e32 v137, v140, v137
	v_mul_f32_e32 v140, v139, v137
	v_fma_f32 v141, -v136, v140, v139
	v_fmac_f32_e32 v140, v141, v137
	v_cvt_f32_i32_e32 v141, v146
	v_fma_f32 v136, -v136, v140, v139
	v_cvt_f32_u32_e32 v139, s22
	s_or_b32 s22, s46, 3
	v_div_fmas_f32 v136, v136, v137, v140
	v_cvt_f32_u32_e32 v140, s22
	v_div_scale_f32 v147, s[22:23], s6, s6, v141
	v_rcp_f32_e32 v148, v147
	v_div_fixup_f32 v1, v136, s6, v1
	v_mul_f32_e32 v137, 0xbfb8aa3b, v1
	v_fmamk_f32 v1, v138, 0xbc44ade8, v189
	v_fma_f32 v149, -v147, v148, 1.0
	v_fmac_f32_e32 v148, v149, v148
	v_div_scale_f32 v149, vcc, v141, s6, v141
	v_mul_f32_e32 v150, v149, v148
	v_fma_f32 v151, -v147, v150, v149
	v_fmac_f32_e32 v150, v151, v148
	v_fma_f32 v147, -v147, v150, v149
	v_div_fmas_f32 v147, v147, v148, v150
	v_add_u32_e32 v148, 0x200, v2
	v_cvt_f32_i32_e32 v149, v148
	s_lshl_b32 s0, s46, 14
	s_lshl_b32 s1, s44, 24
	v_mul_f32_e64 v136, |v1|, v137
	s_or_b32 s24, s1, s0
	s_or_b32 s0, s46, 1
	v_exp_f32_e32 v142, v136
	v_cvt_f32_u32_e32 v136, s0
	v_div_scale_f32 v152, s[22:23], s6, s6, v149
	v_div_fixup_f32 v141, v147, s6, v141
	v_rcp_f32_e32 v154, v152
	v_mul_f32_e32 v141, 0xbfb8aa3b, v141
	v_fmamk_f32 v138, v136, 0xbc44ade8, v189
	v_mul_f32_e64 v147, |v1|, v141
	v_exp_f32_e32 v150, v147
	v_mul_f32_e64 v147, |v138|, v141
	v_exp_f32_e32 v151, v147
	v_fma_f32 v147, -v152, v154, 1.0
	v_fmac_f32_e32 v154, v147, v154
	v_div_scale_f32 v147, vcc, v149, s6, v149
	v_mul_f32_e32 v155, v147, v154
	v_mul_f32_e64 v136, |v138|, v137
	v_fma_f32 v153, -v152, v155, v147
	v_readlane_b32 s4, v246, 14
	s_or_b32 s0, s24, 0x2000000
	v_exp_f32_e32 v143, v136
	v_fmac_f32_e32 v155, v153, v154
	s_or_b32 s22, s24, 0x4000
	s_or_b32 s28, s24, 0x2004000
	s_or_b32 s34, s24, 0x8000
	s_or_b32 s36, s24, 0x2008000
	s_or_b32 s38, s24, 0xc000
	s_or_b32 s40, s24, 0x200c000
	v_readlane_b32 s5, v246, 15
	v_fma_f32 v147, -v152, v155, v147
	s_add_u32 s42, s4, s24
	v_div_fmas_f32 v156, v147, v154, v155
	v_ashrrev_i32_e32 v147, 31, v146
	s_addc_u32 s43, s5, 0
	v_lshl_add_u64 v[134:135], v[2:3], 2, s[4:5]
	v_lshl_add_u64 v[146:147], v[146:147], 2, s[42:43]
	v_pk_mul_f32 v[128:129], v[150:151], v[128:129]
	s_mov_b64 s[4:5], 0x400
	v_lshl_add_u64 v[144:145], v[134:135], 0, s[24:25]
	s_mov_b32 s1, s25
	v_fmamk_f32 v139, v139, 0xbc44ade8, v189
	v_fmamk_f32 v140, v140, 0xbc44ade8, v189
	s_mov_b32 s23, s25
	s_mov_b32 s29, s25
	v_pk_mul_f32 v[132:133], v[142:143], v[132:133]
	global_store_dword v[146:147], v128, off
	v_lshl_add_u64 v[146:147], v[134:135], 0, s[4:5]
	v_lshl_add_u64 v[152:153], v[134:135], 0, s[0:1]
	v_lshl_add_u64 v[154:155], v[134:135], 0, s[22:23]
	global_store_dword v[144:145], v132, off
	v_lshl_add_u64 v[144:145], v[134:135], 0, s[28:29]
	v_pk_mul_f32 v[130:131], v[142:143], v[130:131]
	v_mul_f32_e64 v142, |v139|, v141
	v_mul_f32_e64 v141, |v140|, v141
	v_pk_mul_f32 v[126:127], v[150:151], v[126:127]
	v_lshl_add_u64 v[150:151], v[146:147], 0, s[0:1]
	v_exp_f32_e32 v143, v141
	global_store_dword v[152:153], v130, off
	global_store_dword v[154:155], v133, off
	v_and_b32_e32 v133, 0x7fffffff, v133
	v_and_b32_e32 v132, 0x7fffffff, v132
	global_store_dword v[144:145], v131, off
	v_and_b32_e32 v131, 0x7fffffff, v131
	v_and_b32_e32 v130, 0x7fffffff, v130
	global_store_dword v[150:151], v126, off
	v_lshl_add_u64 v[150:151], v[146:147], 0, s[22:23]
	v_div_fixup_f32 v141, v156, s6, v149
	v_pk_add_f32 v[130:131], v[132:133], v[130:131]
	v_mul_f32_e32 v141, 0xbfb8aa3b, v141
	global_store_dword v[150:151], v129, off
	v_and_b32_e32 v129, 0x7fffffff, v129
	v_and_b32_e32 v128, 0x7fffffff, v128
	v_mul_f32_e64 v149, |v1|, v141
	v_pk_add_f32 v[128:129], v[128:129], v[130:131]
	v_mul_f32_e64 v131, |v138|, v141
	v_exp_f32_e32 v130, v149
	v_exp_f32_e32 v131, v131
	v_ashrrev_i32_e32 v149, 31, v148
	v_lshl_add_u64 v[148:149], v[148:149], 2, s[42:43]
	s_mov_b64 s[48:49], 0x800
	v_pk_mul_f32 v[116:117], v[130:131], v[116:117]
	v_lshl_add_u64 v[156:157], v[146:147], 0, s[28:29]
	global_store_dword v[148:149], v116, off
	v_lshl_add_u64 v[148:149], v[134:135], 0, s[48:49]
	global_store_dword v[156:157], v127, off
	v_and_b32_e32 v127, 0x7fffffff, v127
	v_and_b32_e32 v126, 0x7fffffff, v126
	v_pk_mul_f32 v[114:115], v[130:131], v[114:115]
	v_lshl_add_u64 v[130:131], v[148:149], 0, s[0:1]
	v_pk_add_f32 v[126:127], v[126:127], v[128:129]
	global_store_dword v[130:131], v114, off
	v_and_b32_e32 v131, 0x7fffffff, v117
	v_and_b32_e32 v130, 0x7fffffff, v116
	v_pk_add_f32 v[126:127], v[130:131], v[126:127]
	v_lshl_add_u64 v[130:131], v[148:149], 0, s[22:23]
	global_store_dword v[130:131], v117, off
	v_and_b32_e32 v117, 0x7fffffff, v115
	v_and_b32_e32 v116, 0x7fffffff, v114
	v_pk_add_f32 v[126:127], v[116:117], v[126:127]
	v_lshl_add_u64 v[116:117], v[148:149], 0, s[28:29]
	v_mul_f32_e64 v136, |v139|, v137
	v_mul_f32_e64 v137, |v140|, v137
	global_store_dword v[116:117], v115, off
	v_mul_f32_e64 v114, |v139|, v141
	v_mul_f32_e64 v115, |v140|, v141
	v_exp_f32_e32 v136, v136
	v_exp_f32_e32 v137, v137
	v_exp_f32_e32 v114, v114
	v_exp_f32_e32 v115, v115
	s_mov_b32 s35, s25
	v_lshl_add_u64 v[152:153], v[134:135], 0, s[34:35]
	s_mov_b32 s39, s25
	v_lshl_add_u64 v[116:117], v[148:149], 0, s[34:35]
	v_pk_mul_f32 v[124:125], v[136:137], v[124:125]
	v_pk_mul_f32 v[112:113], v[114:115], v[112:113]
	v_exp_f32_e32 v142, v142
	global_store_dword v[152:153], v124, off
	v_lshl_add_u64 v[152:153], v[148:149], 0, s[38:39]
	global_store_dword v[116:117], v112, off
	v_pk_mul_f32 v[114:115], v[114:115], v[110:111]
	v_and_b32_e32 v110, 0x7fffffff, v112
	v_add_u32_e32 v112, 0x300, v2
	v_and_b32_e32 v111, 0x7fffffff, v113
	global_store_dword v[152:153], v113, off
	v_cvt_f32_i32_e32 v113, v112
	s_mov_b32 s37, s25
	v_lshl_add_u64 v[144:145], v[134:135], 0, s[38:39]
	s_mov_b32 s41, s25
	v_pk_mul_f32 v[122:123], v[136:137], v[122:123]
	v_lshl_add_u64 v[154:155], v[134:135], 0, s[36:37]
	v_lshl_add_u64 v[132:133], v[134:135], 0, s[40:41]
	v_lshl_add_u64 v[130:131], v[148:149], 0, s[36:37]
	v_and_b32_e32 v137, 0x7fffffff, v125
	v_and_b32_e32 v136, 0x7fffffff, v124
	global_store_dword v[144:145], v125, off
	v_and_b32_e32 v125, 0x7fffffff, v123
	v_and_b32_e32 v124, 0x7fffffff, v122
	v_pk_mul_f32 v[120:121], v[142:143], v[120:121]
	v_lshl_add_u64 v[150:151], v[146:147], 0, s[34:35]
	v_lshl_add_u64 v[156:157], v[146:147], 0, s[36:37]
	v_lshl_add_u64 v[128:129], v[146:147], 0, s[38:39]
	global_store_dword v[154:155], v122, off
	v_pk_add_f32 v[124:125], v[136:137], v[124:125]
	global_store_dword v[132:133], v123, off
	v_pk_mul_f32 v[118:119], v[142:143], v[118:119]
	v_and_b32_e32 v123, 0x7fffffff, v121
	v_and_b32_e32 v122, 0x7fffffff, v120
	global_store_dword v[130:131], v114, off
	v_and_b32_e32 v116, 0x7fffffff, v114
	v_div_scale_f32 v114, s[48:49], s6, s6, v113
	global_store_dword v[150:151], v120, off
	global_store_dword v[156:157], v118, off
	v_pk_add_f32 v[122:123], v[122:123], v[124:125]
	global_store_dword v[128:129], v121, off
	v_and_b32_e32 v121, 0x7fffffff, v119
	v_and_b32_e32 v120, 0x7fffffff, v118
	v_rcp_f32_e32 v118, v114
	v_pk_add_f32 v[120:121], v[120:121], v[122:123]
	v_and_b32_e32 v117, 0x7fffffff, v115
	v_pk_add_f32 v[110:111], v[110:111], v[120:121]
	s_mov_b64 s[48:49], 0xc00
	v_pk_add_f32 v[110:111], v[116:117], v[110:111]
	v_lshl_add_u64 v[116:117], v[148:149], 0, s[40:41]
	global_store_dword v[116:117], v115, off
	v_fma_f32 v115, -v114, v118, 1.0
	v_fmac_f32_e32 v118, v115, v118
	v_div_scale_f32 v115, vcc, v113, s6, v113
	v_mul_f32_e32 v116, v115, v118
	v_fma_f32 v117, -v114, v116, v115
	v_fmac_f32_e32 v116, v117, v118
	v_fma_f32 v114, -v114, v116, v115
	v_div_fmas_f32 v114, v114, v118, v116
	v_div_fixup_f32 v113, v114, s6, v113
	v_mul_f32_e32 v120, 0xbfb8aa3b, v113
	v_mul_f32_e64 v114, |v1|, v120
	v_mul_f32_e64 v115, |v138|, v120
	v_exp_f32_e32 v114, v114
	v_exp_f32_e32 v115, v115
	v_ashrrev_i32_e32 v113, 31, v112
	v_lshl_add_u64 v[116:117], v[134:135], 0, s[48:49]
	v_lshl_add_u64 v[112:113], v[112:113], 2, s[42:43]
	v_pk_mul_f32 v[104:105], v[114:115], v[104:105]
	global_store_dword v[112:113], v104, off
	v_lshl_add_u64 v[112:113], v[116:117], 0, s[22:23]
	v_and_b32_e32 v123, 0x7fffffff, v105
	v_and_b32_e32 v122, 0x7fffffff, v104
	global_store_dword v[112:113], v105, off
	v_mul_f32_e64 v104, |v139|, v120
	v_mul_f32_e64 v105, |v140|, v120
	v_exp_f32_e32 v104, v104
	v_exp_f32_e32 v105, v105
	v_pk_mul_f32 v[124:125], v[114:115], v[102:103]
	v_lshl_add_u64 v[102:103], v[116:117], 0, s[28:29]
	global_store_dword v[102:103], v125, off
	v_lshl_add_u64 v[102:103], v[116:117], 0, s[34:35]
	v_pk_mul_f32 v[108:109], v[104:105], v[108:109]
	global_store_dword v[102:103], v108, off
	v_and_b32_e32 v102, 0x7fffffff, v108
	v_add_u32_e32 v108, 0x400, v2
	v_cvt_f32_i32_e32 v108, v108
	v_lshl_add_u64 v[114:115], v[116:117], 0, s[38:39]
	v_and_b32_e32 v103, 0x7fffffff, v109
	global_store_dword v[114:115], v109, off
	v_div_scale_f32 v109, s[42:43], s6, s6, v108
	v_rcp_f32_e32 v114, v109
	v_pk_mul_f32 v[104:105], v[104:105], v[106:107]
	v_lshl_add_u64 v[106:107], v[116:117], 0, s[40:41]
	global_store_dword v[106:107], v105, off
	v_fma_f32 v106, -v109, v114, 1.0
	v_fmac_f32_e32 v114, v106, v114
	v_div_scale_f32 v106, vcc, v108, s6, v108
	v_lshl_add_u64 v[112:113], v[116:117], 0, s[36:37]
	v_mul_f32_e32 v107, v106, v114
	global_store_dword v[112:113], v104, off
	v_fma_f32 v112, -v109, v107, v106
	v_fmac_f32_e32 v107, v112, v114
	v_lshl_add_u64 v[146:147], v[146:147], 0, s[40:41]
	v_fma_f32 v106, -v109, v107, v106
	global_store_dword v[146:147], v119, off
	v_lshl_add_u64 v[118:119], v[116:117], 0, s[0:1]
	v_div_fmas_f32 v106, v106, v114, v107
	v_add_u32_e32 v114, 0x500, v2
	global_store_dword v[118:119], v124, off
	v_cvt_f32_i32_e32 v118, v114
	v_div_fixup_f32 v106, v106, s6, v108
	v_mul_f32_e32 v107, 0xbfb8aa3b, v106
	v_mul_f32_e64 v106, |v1|, v107
	v_div_scale_f32 v119, s[42:43], s6, s6, v118
	v_rcp_f32_e32 v120, v119
	s_mov_b64 s[42:43], 0x1400
	v_exp_f32_e32 v128, v106
	v_mul_f32_e64 v106, |v138|, v107
	v_fma_f32 v121, -v119, v120, 1.0
	v_fmac_f32_e32 v120, v121, v120
	v_div_scale_f32 v121, vcc, v118, s6, v118
	v_mul_f32_e32 v141, v121, v120
	v_fma_f32 v144, -v119, v141, v121
	v_fmac_f32_e32 v141, v144, v120
	v_fma_f32 v119, -v119, v141, v121
	v_div_fmas_f32 v119, v119, v120, v141
	v_add_u32_e32 v120, 0x600, v2
	v_cvt_f32_i32_e32 v120, v120
	v_lshl_add_u64 v[144:145], v[134:135], 0, s[42:43]
	v_div_fixup_f32 v118, v119, s6, v118
	v_mul_f32_e32 v119, 0xbfb8aa3b, v118
	v_div_scale_f32 v121, s[42:43], s6, s6, v120
	v_rcp_f32_e32 v141, v121
	v_exp_f32_e32 v129, v106
	v_mul_f32_e64 v118, |v1|, v119
	v_exp_f32_e32 v146, v118
	v_fma_f32 v148, -v121, v141, 1.0
	v_fmac_f32_e32 v141, v148, v141
	v_div_scale_f32 v148, vcc, v120, s6, v120
	v_mul_f32_e32 v149, v148, v141
	v_fma_f32 v150, -v121, v149, v148
	v_fmac_f32_e32 v149, v150, v141
	v_fma_f32 v121, -v121, v149, v148
	v_div_fmas_f32 v121, v121, v141, v149
	v_add_u32_e32 v141, 0x700, v2
	v_cvt_f32_i32_e32 v141, v141
	v_div_fixup_f32 v120, v121, s6, v120
	v_mul_f32_e64 v118, |v138|, v119
	v_mul_f32_e32 v121, 0xbfb8aa3b, v120
	v_div_scale_f32 v150, s[42:43], s6, s6, v141
	v_rcp_f32_e32 v151, v150
	s_mov_b64 s[4:5], 0x1000
	v_exp_f32_e32 v147, v118
	v_mul_f32_e64 v120, |v1|, v121
	v_fma_f32 v152, -v150, v151, 1.0
	v_fmac_f32_e32 v151, v152, v151
	v_div_scale_f32 v152, vcc, v141, s6, v141
	v_mul_f32_e32 v153, v152, v151
	v_fma_f32 v154, -v150, v153, v152
	v_fmac_f32_e32 v153, v154, v151
	v_fma_f32 v150, -v150, v153, v152
	v_div_fmas_f32 v150, v150, v151, v153
	v_div_fixup_f32 v141, v150, s6, v141
	v_add_u32_e32 v150, 0x800, v2
	v_cvt_f32_i32_e32 v156, v150
	v_lshl_add_u64 v[112:113], v[134:135], 0, s[4:5]
	v_exp_f32_e32 v148, v120
	v_mul_f32_e64 v120, |v138|, v121
	v_div_scale_f32 v152, s[42:43], s6, s6, v156
	v_rcp_f32_e32 v154, v152
	v_lshl_add_u64 v[130:131], v[112:113], 0, s[24:25]
	v_lshl_add_u64 v[136:137], v[112:113], 0, s[22:23]
	v_exp_f32_e32 v149, v120
	v_fma_f32 v153, -v152, v154, 1.0
	v_fmac_f32_e32 v154, v153, v154
	v_div_scale_f32 v153, vcc, v156, s6, v156
	v_mul_f32_e32 v155, v153, v154
	v_fma_f32 v157, -v152, v155, v153
	v_pk_add_f32 v[122:123], v[122:123], v[126:127]
	v_and_b32_e32 v125, 0x7fffffff, v125
	v_and_b32_e32 v124, 0x7fffffff, v124
	v_pk_mul_f32 v[100:101], v[128:129], v[100:101]
	v_lshl_add_u64 v[132:133], v[112:113], 0, s[0:1]
	v_lshl_add_u64 v[142:143], v[112:113], 0, s[28:29]
	v_fmac_f32_e32 v155, v157, v154
	v_pk_add_f32 v[122:123], v[124:125], v[122:123]
	global_store_dword v[130:131], v100, off
	v_pk_mul_f32 v[96:97], v[128:129], v[96:97]
	global_store_dword v[136:137], v101, off
	v_and_b32_e32 v101, 0x7fffffff, v101
	v_and_b32_e32 v100, 0x7fffffff, v100
	v_fma_f32 v157, -v152, v155, v153
	v_lshl_add_u64 v[152:153], v[144:145], 0, s[24:25]
	v_lshl_add_u64 v[126:127], v[144:145], 0, s[22:23]
	global_store_dword v[132:133], v96, off
	v_pk_add_f32 v[100:101], v[100:101], v[122:123]
	s_mov_b64 s[42:43], 0x1800
	global_store_dword v[142:143], v97, off
	v_and_b32_e32 v97, 0x7fffffff, v97
	v_and_b32_e32 v96, 0x7fffffff, v96
	v_pk_mul_f32 v[98:99], v[146:147], v[98:99]
	v_mul_f32_e32 v141, 0xbfb8aa3b, v141
	v_div_fmas_f32 v157, v157, v154, v155
	v_lshl_add_u64 v[154:155], v[144:145], 0, s[0:1]
	v_lshl_add_u64 v[130:131], v[144:145], 0, s[28:29]
	v_lshl_add_u64 v[122:123], v[134:135], 0, s[42:43]
	v_pk_add_f32 v[96:97], v[96:97], v[100:101]
	global_store_dword v[152:153], v98, off
	v_pk_mul_f32 v[94:95], v[146:147], v[94:95]
	global_store_dword v[126:127], v99, off
	v_and_b32_e32 v99, 0x7fffffff, v99
	v_and_b32_e32 v98, 0x7fffffff, v98
	v_mul_f32_e64 v150, |v1|, v141
	v_mul_f32_e64 v151, |v138|, v141
	v_mul_f32_e64 v124, |v139|, v141
	v_mul_f32_e64 v125, |v140|, v141
	v_lshl_add_u64 v[142:143], v[122:123], 0, s[24:25]
	v_lshl_add_u64 v[152:153], v[122:123], 0, s[22:23]
	global_store_dword v[154:155], v94, off
	v_pk_add_f32 v[96:97], v[98:99], v[96:97]
	global_store_dword v[130:131], v95, off
	v_and_b32_e32 v95, 0x7fffffff, v95
	v_and_b32_e32 v94, 0x7fffffff, v94
	v_pk_mul_f32 v[92:93], v[148:149], v[92:93]
	v_div_fixup_f32 v141, v157, s6, v156
	v_exp_f32_e32 v150, v150
	v_exp_f32_e32 v151, v151
	v_pk_add_f32 v[94:95], v[94:95], v[96:97]
	global_store_dword v[142:143], v92, off
	global_store_dword v[152:153], v93, off
	v_and_b32_e32 v93, 0x7fffffff, v93
	v_and_b32_e32 v92, 0x7fffffff, v92
	v_mul_f32_e32 v141, 0xbfb8aa3b, v141
	v_pk_add_f32 v[92:93], v[92:93], v[94:95]
	v_mul_f32_e64 v94, |v1|, v141
	v_mul_f32_e64 v95, |v138|, v141
	s_mov_b64 s[42:43], 0x1c00
	v_exp_f32_e32 v94, v94
	v_exp_f32_e32 v95, v95
	v_lshl_add_u64 v[100:101], v[122:123], 0, s[0:1]
	v_lshl_add_u64 v[146:147], v[122:123], 0, s[28:29]
	v_lshl_add_u64 v[130:131], v[134:135], 0, s[42:43]
	v_pk_mul_f32 v[90:91], v[148:149], v[90:91]
	v_mul_f32_e64 v106, |v139|, v107
	v_mul_f32_e64 v107, |v140|, v107
	v_lshl_add_u64 v[142:143], v[130:131], 0, s[0:1]
	global_store_dword v[100:101], v90, off
	global_store_dword v[146:147], v91, off
	v_and_b32_e32 v91, 0x7fffffff, v91
	v_and_b32_e32 v90, 0x7fffffff, v90
	v_pk_mul_f32 v[86:87], v[150:151], v[86:87]
	v_pk_mul_f32 v[82:83], v[150:151], v[82:83]
	v_exp_f32_e32 v106, v106
	v_exp_f32_e32 v107, v107
	v_lshl_add_u64 v[96:97], v[130:131], 0, s[24:25]
	v_lshl_add_u64 v[148:149], v[130:131], 0, s[22:23]
	v_lshl_add_u64 v[156:157], v[130:131], 0, s[28:29]
	v_pk_add_f32 v[90:91], v[90:91], v[92:93]
	global_store_dword v[142:143], v82, off
	v_and_b32_e32 v143, 0x7fffffff, v87
	v_and_b32_e32 v142, 0x7fffffff, v86
	v_mul_f32_e64 v118, |v139|, v119
	v_mul_f32_e64 v119, |v140|, v119
	s_mov_b64 s[42:43], 0x2000
	global_store_dword v[96:97], v86, off
	v_pk_add_f32 v[90:91], v[142:143], v[90:91]
	global_store_dword v[148:149], v87, off
	v_and_b32_e32 v87, 0x7fffffff, v83
	v_and_b32_e32 v86, 0x7fffffff, v82
	global_store_dword v[156:157], v83, off
	v_pk_mul_f32 v[82:83], v[94:95], v[76:77]
	v_exp_f32_e32 v118, v118
	v_exp_f32_e32 v119, v119
	v_lshl_add_u64 v[92:93], v[134:135], 0, s[42:43]
	v_pk_add_f32 v[86:87], v[86:87], v[90:91]
	v_and_b32_e32 v77, 0x7fffffff, v83
	v_and_b32_e32 v76, 0x7fffffff, v82
	v_mul_f32_e64 v120, |v139|, v121
	v_mul_f32_e64 v121, |v140|, v121
	v_lshl_add_u64 v[96:97], v[92:93], 0, s[24:25]
	v_pk_add_f32 v[76:77], v[76:77], v[86:87]
	v_lshl_add_u64 v[86:87], v[92:93], 0, s[22:23]
	v_exp_f32_e32 v120, v120
	v_exp_f32_e32 v121, v121
	global_store_dword v[96:97], v82, off
	global_store_dword v[86:87], v83, off
	v_pk_mul_f32 v[82:83], v[94:95], v[78:79]
	v_pk_add_f32 v[94:95], v[102:103], v[110:111]
	v_and_b32_e32 v97, 0x7fffffff, v105
	v_and_b32_e32 v96, 0x7fffffff, v104
	v_pk_mul_f32 v[88:89], v[106:107], v[88:89]
	v_lshl_add_u64 v[108:109], v[112:113], 0, s[34:35]
	v_lshl_add_u64 v[116:117], v[112:113], 0, s[36:37]
	v_lshl_add_u64 v[114:115], v[112:113], 0, s[38:39]
	v_lshl_add_u64 v[112:113], v[112:113], 0, s[40:41]
	v_lshl_add_u64 v[150:151], v[92:93], 0, s[0:1]
	v_lshl_add_u64 v[86:87], v[92:93], 0, s[28:29]
	v_pk_add_f32 v[94:95], v[96:97], v[94:95]
	v_pk_mul_f32 v[62:63], v[106:107], v[62:63]
	v_and_b32_e32 v97, 0x7fffffff, v89
	v_and_b32_e32 v96, 0x7fffffff, v88
	v_exp_f32_e32 v124, v124
	v_exp_f32_e32 v125, v125
	global_store_dword v[150:151], v82, off
	v_and_b32_e32 v79, 0x7fffffff, v83
	v_and_b32_e32 v78, 0x7fffffff, v82
	global_store_dword v[86:87], v83, off
	v_mul_f32_e64 v82, |v139|, v141
	v_mul_f32_e64 v83, |v140|, v141
	global_store_dword v[108:109], v88, off
	global_store_dword v[116:117], v62, off
	v_pk_add_f32 v[94:95], v[96:97], v[94:95]
	global_store_dword v[114:115], v89, off
	v_and_b32_e32 v89, 0x7fffffff, v63
	v_and_b32_e32 v88, 0x7fffffff, v62
	global_store_dword v[112:113], v63, off
	v_pk_mul_f32 v[62:63], v[118:119], v[84:85]
	v_lshl_add_u64 v[128:129], v[144:145], 0, s[34:35]
	v_lshl_add_u64 v[136:137], v[144:145], 0, s[38:39]
	v_exp_f32_e32 v82, v82
	v_exp_f32_e32 v83, v83
	v_pk_add_f32 v[88:89], v[88:89], v[94:95]
	v_pk_mul_f32 v[80:81], v[118:119], v[80:81]
	v_and_b32_e32 v85, 0x7fffffff, v63
	v_and_b32_e32 v84, 0x7fffffff, v62
	v_lshl_add_u64 v[132:133], v[144:145], 0, s[36:37]
	v_lshl_add_u64 v[144:145], v[144:145], 0, s[40:41]
	global_store_dword v[128:129], v62, off
	v_pk_add_f32 v[84:85], v[84:85], v[88:89]
	global_store_dword v[136:137], v63, off
	v_and_b32_e32 v63, 0x7fffffff, v81
	v_and_b32_e32 v62, 0x7fffffff, v80
	v_pk_mul_f32 v[74:75], v[120:121], v[74:75]
	v_lshl_add_u64 v[154:155], v[122:123], 0, s[34:35]
	v_lshl_add_u64 v[98:99], v[122:123], 0, s[38:39]
	global_store_dword v[132:133], v80, off
	v_pk_add_f32 v[62:63], v[62:63], v[84:85]
	global_store_dword v[144:145], v81, off
	v_pk_mul_f32 v[72:73], v[120:121], v[72:73]
	v_and_b32_e32 v81, 0x7fffffff, v75
	v_and_b32_e32 v80, 0x7fffffff, v74
	v_lshl_add_u64 v[126:127], v[122:123], 0, s[36:37]
	v_lshl_add_u64 v[122:123], v[122:123], 0, s[40:41]
	global_store_dword v[154:155], v74, off
	v_pk_add_f32 v[62:63], v[80:81], v[62:63]
	global_store_dword v[98:99], v75, off
	v_and_b32_e32 v75, 0x7fffffff, v73
	v_and_b32_e32 v74, 0x7fffffff, v72
	v_pk_mul_f32 v[70:71], v[124:125], v[70:71]
	v_lshl_add_u64 v[100:101], v[130:131], 0, s[34:35]
	v_lshl_add_u64 v[152:153], v[130:131], 0, s[36:37]
	v_lshl_add_u64 v[146:147], v[130:131], 0, s[38:39]
	v_lshl_add_u64 v[86:87], v[92:93], 0, s[34:35]
	global_store_dword v[126:127], v72, off
	v_pk_add_f32 v[62:63], v[74:75], v[62:63]
	global_store_dword v[122:123], v73, off
	v_pk_mul_f32 v[68:69], v[124:125], v[68:69]
	v_and_b32_e32 v73, 0x7fffffff, v71
	v_and_b32_e32 v72, 0x7fffffff, v70
	v_pk_mul_f32 v[64:65], v[82:83], v[64:65]
	global_store_dword v[100:101], v70, off
	global_store_dword v[152:153], v68, off
	v_pk_add_f32 v[62:63], v[72:73], v[62:63]
	global_store_dword v[146:147], v71, off
	v_and_b32_e32 v71, 0x7fffffff, v69
	v_and_b32_e32 v70, 0x7fffffff, v68
	global_store_dword v[86:87], v64, off
	v_and_b32_e32 v68, 0x7fffffff, v64
	v_add_u32_e32 v64, 0x900, v2
	v_pk_add_f32 v[62:63], v[70:71], v[62:63]
	v_cvt_f32_i32_e32 v70, v64
	v_lshl_add_u64 v[130:131], v[130:131], 0, s[40:41]
	v_lshl_add_u64 v[90:91], v[92:93], 0, s[36:37]
	global_store_dword v[130:131], v69, off
	v_div_scale_f32 v71, s[42:43], s6, s6, v70
	v_rcp_f32_e32 v72, v71
	v_and_b32_e32 v69, 0x7fffffff, v65
	v_pk_mul_f32 v[66:67], v[82:83], v[66:67]
	v_pk_add_f32 v[62:63], v[68:69], v[62:63]
	v_lshl_add_u64 v[68:69], v[92:93], 0, s[38:39]
	global_store_dword v[90:91], v66, off
	v_and_b32_e32 v64, 0x7fffffff, v66
	v_fma_f32 v66, -v71, v72, 1.0
	global_store_dword v[68:69], v65, off
	v_lshl_add_u64 v[68:69], v[92:93], 0, s[40:41]
	v_fmac_f32_e32 v72, v66, v72
	v_div_scale_f32 v66, vcc, v70, s6, v70
	v_and_b32_e32 v65, 0x7fffffff, v67
	global_store_dword v[68:69], v67, off
	v_mul_f32_e32 v67, v66, v72
	v_fma_f32 v68, -v71, v67, v66
	v_fmac_f32_e32 v67, v68, v72
	v_fma_f32 v66, -v71, v67, v66
	v_div_fmas_f32 v66, v66, v72, v67
	v_div_fixup_f32 v66, v66, s6, v70
	v_mul_f32_e32 v84, 0xbfb8aa3b, v66
	v_mul_f32_e64 v66, |v1|, v84
	v_exp_f32_e32 v68, v66
	v_mul_f32_e64 v66, |v138|, v84
	v_exp_f32_e32 v69, v66
	s_mov_b64 s[42:43], 0x2400
	v_lshl_add_u64 v[70:71], v[134:135], 0, s[42:43]
	v_lshl_add_u64 v[82:83], v[70:71], 0, s[34:35]
	v_pk_mul_f32 v[74:75], v[68:69], v[58:59]
	v_lshl_add_u64 v[58:59], v[70:71], 0, s[22:23]
	global_store_dword v[58:59], v75, off
	v_mul_f32_e64 v58, |v139|, v84
	v_mul_f32_e64 v59, |v140|, v84
	v_add_u32_e32 v84, 0xa00, v2
	v_cvt_f32_i32_e32 v84, v84
	v_exp_f32_e32 v58, v58
	v_exp_f32_e32 v59, v59
	v_add_u32_e32 v98, 0xb00, v2
	v_div_scale_f32 v85, s[42:43], s6, s6, v84
	v_rcp_f32_e32 v86, v85
	v_pk_mul_f32 v[60:61], v[58:59], v[60:61]
	global_store_dword v[82:83], v60, off
	v_lshl_add_u64 v[82:83], v[70:71], 0, s[38:39]
	global_store_dword v[82:83], v61, off
	v_fma_f32 v82, -v85, v86, 1.0
	v_fmac_f32_e32 v86, v82, v86
	v_div_scale_f32 v82, vcc, v84, s6, v84
	v_mul_f32_e32 v83, v82, v86
	v_fma_f32 v87, -v85, v83, v82
	v_fmac_f32_e32 v83, v87, v86
	v_cvt_f32_i32_e32 v102, v98
	v_fma_f32 v82, -v85, v83, v82
	v_div_fmas_f32 v82, v82, v86, v83
	v_div_fixup_f32 v82, v82, s6, v84
	s_mov_b64 s[42:43], 0x2800
	v_mul_f32_e32 v95, 0xbfb8aa3b, v82
	v_lshl_add_u64 v[82:83], v[134:135], 0, s[42:43]
	v_div_scale_f32 v103, s[42:43], s6, s6, v102
	v_rcp_f32_e32 v104, v103
	v_add_u32_e32 v118, 0xc00, v2
	v_cvt_f32_i32_e32 v122, v118
	s_mov_b64 s[42:43], 0x2c00
	v_fma_f32 v105, -v103, v104, 1.0
	v_fmac_f32_e32 v104, v105, v104
	v_div_scale_f32 v105, vcc, v102, s6, v102
	v_mul_f32_e32 v106, v105, v104
	v_fma_f32 v107, -v103, v106, v105
	v_fmac_f32_e32 v106, v107, v104
	v_fma_f32 v103, -v103, v106, v105
	v_div_fmas_f32 v103, v103, v104, v106
	v_div_fixup_f32 v102, v103, s6, v102
	v_mul_f32_e32 v115, 0xbfb8aa3b, v102
	v_lshl_add_u64 v[102:103], v[134:135], 0, s[42:43]
	v_div_scale_f32 v123, s[42:43], s6, s6, v122
	v_rcp_f32_e32 v124, v123
	v_add_u32_e32 v141, 0xd00, v2
	v_cvt_f32_i32_e32 v141, v141
	s_mov_b64 s[42:43], 0x3000
	v_fma_f32 v125, -v123, v124, 1.0
	v_fmac_f32_e32 v124, v125, v124
	v_div_scale_f32 v125, vcc, v122, s6, v122
	v_mul_f32_e32 v126, v125, v124
	v_fma_f32 v127, -v123, v126, v125
	v_fmac_f32_e32 v126, v127, v124
	v_fma_f32 v123, -v123, v126, v125
	v_div_fmas_f32 v123, v123, v124, v126
	v_div_fixup_f32 v122, v123, s6, v122
	v_mul_f32_e32 v137, 0xbfb8aa3b, v122
	v_lshl_add_u64 v[122:123], v[134:135], 0, s[42:43]
	v_div_scale_f32 v148, s[42:43], s6, s6, v141
	v_rcp_f32_e32 v149, v148
	v_mul_f32_e64 v84, |v1|, v95
	v_mul_f32_e64 v85, |v138|, v95
	v_exp_f32_e32 v84, v84
	v_fma_f32 v150, -v148, v149, 1.0
	v_fmac_f32_e32 v149, v150, v149
	v_div_scale_f32 v150, vcc, v141, s6, v141
	v_mul_f32_e32 v151, v150, v149
	v_fma_f32 v152, -v148, v151, v150
	v_exp_f32_e32 v85, v85
	v_fmac_f32_e32 v151, v152, v149
	v_mul_f32_e64 v104, |v1|, v115
	v_mul_f32_e64 v105, |v138|, v115
	v_fma_f32 v148, -v148, v151, v150
	v_exp_f32_e32 v104, v104
	v_exp_f32_e32 v105, v105
	v_div_fmas_f32 v148, v148, v149, v151
	v_lshl_add_u64 v[72:73], v[70:71], 0, s[0:1]
	v_mul_f32_e64 v124, |v1|, v137
	v_mul_f32_e64 v125, |v138|, v137
	v_div_fixup_f32 v141, v148, s6, v141
	v_pk_add_f32 v[76:77], v[78:79], v[76:77]
	v_pk_mul_f32 v[56:57], v[68:69], v[56:57]
	v_and_b32_e32 v69, 0x7fffffff, v75
	v_and_b32_e32 v68, 0x7fffffff, v74
	v_lshl_add_u64 v[80:81], v[70:71], 0, s[28:29]
	v_exp_f32_e32 v124, v124
	v_exp_f32_e32 v125, v125
	v_mul_f32_e32 v141, 0xbfb8aa3b, v141
	global_store_dword v[72:73], v56, off
	v_pk_add_f32 v[68:69], v[68:69], v[76:77]
	v_and_b32_e32 v73, 0x7fffffff, v57
	v_and_b32_e32 v72, 0x7fffffff, v56
	v_pk_mul_f32 v[46:47], v[84:85], v[46:47]
	v_lshl_add_u64 v[86:87], v[82:83], 0, s[24:25]
	v_lshl_add_u64 v[90:91], v[82:83], 0, s[22:23]
	v_mul_f32_e64 v150, |v1|, v141
	v_mul_f32_e64 v151, |v138|, v141
	v_pk_add_f32 v[68:69], v[72:73], v[68:69]
	global_store_dword v[80:81], v57, off
	v_pk_mul_f32 v[54:55], v[84:85], v[54:55]
	v_and_b32_e32 v57, 0x7fffffff, v47
	v_and_b32_e32 v56, 0x7fffffff, v46
	v_lshl_add_u64 v[88:89], v[82:83], 0, s[0:1]
	v_lshl_add_u64 v[92:93], v[82:83], 0, s[28:29]
	v_exp_f32_e32 v150, v150
	v_exp_f32_e32 v151, v151
	global_store_dword v[86:87], v46, off
	v_pk_add_f32 v[56:57], v[56:57], v[68:69]
	global_store_dword v[90:91], v47, off
	v_and_b32_e32 v47, 0x7fffffff, v55
	v_and_b32_e32 v46, 0x7fffffff, v54
	v_pk_mul_f32 v[50:51], v[104:105], v[50:51]
	v_lshl_add_u64 v[106:107], v[102:103], 0, s[24:25]
	v_lshl_add_u64 v[110:111], v[102:103], 0, s[22:23]
	global_store_dword v[88:89], v54, off
	v_pk_add_f32 v[46:47], v[46:47], v[56:57]
	global_store_dword v[92:93], v55, off
	v_pk_mul_f32 v[48:49], v[104:105], v[48:49]
	v_and_b32_e32 v55, 0x7fffffff, v51
	v_and_b32_e32 v54, 0x7fffffff, v50
	v_mul_f32_e64 v94, |v139|, v95
	v_mul_f32_e64 v95, |v140|, v95
	v_lshl_add_u64 v[108:109], v[102:103], 0, s[0:1]
	v_lshl_add_u64 v[112:113], v[102:103], 0, s[28:29]
	global_store_dword v[106:107], v50, off
	v_pk_add_f32 v[46:47], v[54:55], v[46:47]
	global_store_dword v[110:111], v51, off
	v_and_b32_e32 v51, 0x7fffffff, v49
	v_and_b32_e32 v50, 0x7fffffff, v48
	v_pk_mul_f32 v[42:43], v[124:125], v[42:43]
	v_exp_f32_e32 v94, v94
	v_exp_f32_e32 v95, v95
	v_lshl_add_u64 v[126:127], v[122:123], 0, s[24:25]
	v_lshl_add_u64 v[130:131], v[122:123], 0, s[22:23]
	s_mov_b64 s[42:43], 0x3400
	global_store_dword v[108:109], v48, off
	v_pk_add_f32 v[46:47], v[50:51], v[46:47]
	global_store_dword v[112:113], v49, off
	v_pk_mul_f32 v[40:41], v[124:125], v[40:41]
	v_and_b32_e32 v49, 0x7fffffff, v43
	v_and_b32_e32 v48, 0x7fffffff, v42
	v_mul_f32_e64 v114, |v139|, v115
	v_mul_f32_e64 v115, |v140|, v115
	v_lshl_add_u64 v[128:129], v[122:123], 0, s[0:1]
	v_lshl_add_u64 v[132:133], v[122:123], 0, s[28:29]
	v_lshl_add_u64 v[148:149], v[134:135], 0, s[42:43]
	global_store_dword v[126:127], v42, off
	v_pk_add_f32 v[46:47], v[48:49], v[46:47]
	global_store_dword v[130:131], v43, off
	v_and_b32_e32 v43, 0x7fffffff, v41
	v_and_b32_e32 v42, 0x7fffffff, v40
	v_pk_mul_f32 v[34:35], v[150:151], v[34:35]
	v_exp_f32_e32 v114, v114
	v_exp_f32_e32 v115, v115
	v_lshl_add_u64 v[152:153], v[148:149], 0, s[24:25]
	v_lshl_add_u64 v[156:157], v[148:149], 0, s[22:23]
	global_store_dword v[128:129], v40, off
	v_pk_add_f32 v[42:43], v[42:43], v[46:47]
	global_store_dword v[132:133], v41, off
	v_pk_mul_f32 v[32:33], v[150:151], v[32:33]
	v_and_b32_e32 v41, 0x7fffffff, v35
	v_and_b32_e32 v40, 0x7fffffff, v34
	v_lshl_add_u64 v[66:67], v[70:71], 0, s[24:25]
	v_mul_f32_e64 v136, |v139|, v137
	v_mul_f32_e64 v137, |v140|, v137
	global_store_dword v[152:153], v34, off
	v_pk_add_f32 v[40:41], v[40:41], v[42:43]
	global_store_dword v[156:157], v35, off
	v_and_b32_e32 v35, 0x7fffffff, v33
	v_and_b32_e32 v34, 0x7fffffff, v32
	v_pk_add_f32 v[48:49], v[64:65], v[62:63]
	v_pk_mul_f32 v[50:51], v[58:59], v[52:53]
	v_and_b32_e32 v53, 0x7fffffff, v61
	v_and_b32_e32 v52, 0x7fffffff, v60
	global_store_dword v[66:67], v74, off
	v_lshl_add_u64 v[66:67], v[70:71], 0, s[36:37]
	v_lshl_add_u64 v[70:71], v[70:71], 0, s[40:41]
	v_exp_f32_e32 v136, v136
	v_exp_f32_e32 v137, v137
	v_lshl_add_u64 v[154:155], v[148:149], 0, s[0:1]
	v_pk_add_f32 v[34:35], v[34:35], v[40:41]
	v_lshl_add_u64 v[40:41], v[148:149], 0, s[28:29]
	v_pk_add_f32 v[48:49], v[52:53], v[48:49]
	v_and_b32_e32 v53, 0x7fffffff, v51
	v_and_b32_e32 v52, 0x7fffffff, v50
	v_pk_mul_f32 v[22:23], v[94:95], v[22:23]
	v_lshl_add_u64 v[96:97], v[82:83], 0, s[34:35]
	v_lshl_add_u64 v[100:101], v[82:83], 0, s[38:39]
	global_store_dword v[154:155], v32, off
	global_store_dword v[40:41], v33, off
	v_mul_f32_e64 v32, |v139|, v141
	v_mul_f32_e64 v33, |v140|, v141
	global_store_dword v[66:67], v50, off
	v_pk_add_f32 v[48:49], v[52:53], v[48:49]
	global_store_dword v[70:71], v51, off
	v_pk_mul_f32 v[44:45], v[94:95], v[44:45]
	v_and_b32_e32 v51, 0x7fffffff, v23
	v_and_b32_e32 v50, 0x7fffffff, v22
	v_lshl_add_u64 v[98:99], v[82:83], 0, s[36:37]
	v_lshl_add_u64 v[82:83], v[82:83], 0, s[40:41]
	v_exp_f32_e32 v32, v32
	v_exp_f32_e32 v33, v33
	global_store_dword v[96:97], v22, off
	v_pk_add_f32 v[48:49], v[50:51], v[48:49]
	global_store_dword v[100:101], v23, off
	v_and_b32_e32 v23, 0x7fffffff, v45
	v_and_b32_e32 v22, 0x7fffffff, v44
	v_pk_mul_f32 v[38:39], v[114:115], v[38:39]
	v_lshl_add_u64 v[116:117], v[102:103], 0, s[34:35]
	v_lshl_add_u64 v[120:121], v[102:103], 0, s[38:39]
	global_store_dword v[98:99], v44, off
	v_pk_add_f32 v[22:23], v[22:23], v[48:49]
	global_store_dword v[82:83], v45, off
	v_pk_mul_f32 v[36:37], v[114:115], v[36:37]
	v_and_b32_e32 v45, 0x7fffffff, v39
	v_and_b32_e32 v44, 0x7fffffff, v38
	v_lshl_add_u64 v[118:119], v[102:103], 0, s[36:37]
	v_lshl_add_u64 v[102:103], v[102:103], 0, s[40:41]
	global_store_dword v[116:117], v38, off
	v_pk_add_f32 v[22:23], v[44:45], v[22:23]
	global_store_dword v[120:121], v39, off
	v_and_b32_e32 v39, 0x7fffffff, v37
	v_and_b32_e32 v38, 0x7fffffff, v36
	v_pk_mul_f32 v[30:31], v[136:137], v[30:31]
	v_lshl_add_u64 v[142:143], v[122:123], 0, s[34:35]
	v_lshl_add_u64 v[146:147], v[122:123], 0, s[38:39]
	global_store_dword v[118:119], v36, off
	v_pk_add_f32 v[22:23], v[38:39], v[22:23]
	global_store_dword v[102:103], v37, off
	v_pk_mul_f32 v[28:29], v[136:137], v[28:29]
	v_and_b32_e32 v37, 0x7fffffff, v31
	v_and_b32_e32 v36, 0x7fffffff, v30
	v_lshl_add_u64 v[144:145], v[122:123], 0, s[36:37]
	v_lshl_add_u64 v[122:123], v[122:123], 0, s[40:41]
	v_lshl_add_u64 v[40:41], v[148:149], 0, s[34:35]
	global_store_dword v[142:143], v30, off
	v_pk_add_f32 v[22:23], v[36:37], v[22:23]
	global_store_dword v[146:147], v31, off
	v_and_b32_e32 v31, 0x7fffffff, v29
	v_and_b32_e32 v30, 0x7fffffff, v28
	v_pk_mul_f32 v[26:27], v[32:33], v[26:27]
	global_store_dword v[144:145], v28, off
	v_pk_add_f32 v[22:23], v[30:31], v[22:23]
	global_store_dword v[122:123], v29, off
	global_store_dword v[40:41], v26, off
	v_and_b32_e32 v29, 0x7fffffff, v27
	v_and_b32_e32 v28, 0x7fffffff, v26
	v_add_u32_e32 v26, 0xe00, v2
	v_pk_add_f32 v[22:23], v[28:29], v[22:23]
	v_cvt_f32_i32_e32 v28, v26
	v_lshl_add_u64 v[42:43], v[148:149], 0, s[36:37]
	v_pk_mul_f32 v[24:25], v[32:33], v[24:25]
	global_store_dword v[42:43], v24, off
	v_and_b32_e32 v26, 0x7fffffff, v24
	v_div_scale_f32 v24, s[42:43], s6, s6, v28
	v_rcp_f32_e32 v29, v24
	v_lshl_add_u64 v[46:47], v[148:149], 0, s[38:39]
	global_store_dword v[46:47], v27, off
	v_and_b32_e32 v27, 0x7fffffff, v25
	v_pk_add_f32 v[22:23], v[26:27], v[22:23]
	v_lshl_add_u64 v[26:27], v[148:149], 0, s[40:41]
	global_store_dword v[26:27], v25, off
	v_fma_f32 v25, -v24, v29, 1.0
	v_fmac_f32_e32 v29, v25, v29
	v_div_scale_f32 v25, vcc, v28, s6, v28
	v_mul_f32_e32 v26, v25, v29
	v_fma_f32 v27, -v24, v26, v25
	v_fmac_f32_e32 v26, v27, v29
	v_fma_f32 v24, -v24, v26, v25
	v_div_fmas_f32 v24, v24, v29, v26
	v_div_fixup_f32 v24, v24, s6, v28
	v_mul_f32_e32 v36, 0xbfb8aa3b, v24
	v_mul_f32_e64 v24, |v1|, v36
	v_mul_f32_e64 v25, |v138|, v36
	v_exp_f32_e32 v24, v24
	v_exp_f32_e32 v25, v25
	s_mov_b64 s[42:43], 0x3800
	v_lshl_add_u64 v[26:27], v[134:135], 0, s[42:43]
	v_lshl_add_u64 v[28:29], v[26:27], 0, s[24:25]
	v_pk_mul_f32 v[16:17], v[24:25], v[16:17]
	v_pk_mul_f32 v[14:15], v[24:25], v[14:15]
	v_mul_f32_e64 v24, |v139|, v36
	v_mul_f32_e64 v25, |v140|, v36
	v_exp_f32_e32 v24, v24
	v_exp_f32_e32 v25, v25
	v_lshl_add_u64 v[32:33], v[26:27], 0, s[22:23]
	global_store_dword v[28:29], v16, off
	v_and_b32_e32 v29, 0x7fffffff, v17
	v_and_b32_e32 v28, 0x7fffffff, v16
	global_store_dword v[32:33], v17, off
	v_lshl_add_u64 v[16:17], v[26:27], 0, s[28:29]
	global_store_dword v[16:17], v15, off
	v_lshl_add_u64 v[16:17], v[26:27], 0, s[34:35]
	v_pk_mul_f32 v[20:21], v[24:25], v[20:21]
	global_store_dword v[16:17], v20, off
	v_and_b32_e32 v16, 0x7fffffff, v20
	v_add_u32_e32 v20, 0xf00, v2
	v_cvt_f32_i32_e32 v36, v20
	v_pk_mul_f32 v[18:19], v[24:25], v[18:19]
	v_lshl_add_u64 v[32:33], v[26:27], 0, s[38:39]
	v_and_b32_e32 v17, 0x7fffffff, v21
	v_div_scale_f32 v24, s[42:43], s6, s6, v36
	v_rcp_f32_e32 v25, v24
	global_store_dword v[32:33], v21, off
	v_lshl_add_u64 v[20:21], v[26:27], 0, s[40:41]
	global_store_dword v[20:21], v19, off
	v_fma_f32 v20, -v24, v25, 1.0
	v_fmac_f32_e32 v25, v20, v25
	v_div_scale_f32 v20, vcc, v36, s6, v36
	v_lshl_add_u64 v[30:31], v[26:27], 0, s[0:1]
	v_mul_f32_e32 v21, v20, v25
	global_store_dword v[30:31], v14, off
	v_lshl_add_u64 v[30:31], v[26:27], 0, s[36:37]
	v_fma_f32 v26, -v24, v21, v20
	v_fmac_f32_e32 v21, v26, v25
	v_fma_f32 v20, -v24, v21, v20
	v_div_fmas_f32 v20, v20, v25, v21
	v_div_fixup_f32 v20, v20, s6, v36
	v_mul_f32_e32 v39, 0xbfb8aa3b, v20
	v_mul_f32_e64 v1, |v1|, v39
	v_exp_f32_e32 v24, v1
	v_mul_f32_e64 v1, |v138|, v39
	v_exp_f32_e32 v25, v1
	v_mul_f32_e64 v1, |v139|, v39
	v_exp_f32_e32 v38, v1
	v_mul_f32_e64 v1, |v140|, v39
	v_exp_f32_e32 v39, v1
	global_store_dword v[30:31], v18, off
	v_and_b32_e32 v1, 64, v195
	v_pk_add_f32 v[16:17], v[16:17], v[22:23]
	v_and_b32_e32 v19, 0x7fffffff, v19
	v_and_b32_e32 v18, 0x7fffffff, v18
	v_add_u32_e32 v1, 64, v1
	v_xor_b32_e32 v46, 32, v195
	v_pk_add_f32 v[28:29], v[28:29], v[34:35]
	v_and_b32_e32 v15, 0x7fffffff, v15
	v_and_b32_e32 v14, 0x7fffffff, v14
	v_pk_mul_f32 v[10:11], v[24:25], v[10:11]
	v_pk_add_f32 v[16:17], v[18:19], v[16:17]
	v_pk_mul_f32 v[18:19], v[38:39], v[12:13]
	v_cmp_lt_i32_e32 vcc, v46, v1
	v_pk_add_f32 v[14:15], v[14:15], v[28:29]
	v_pk_mul_f32 v[8:9], v[24:25], v[8:9]
	v_and_b32_e32 v25, 0x7fffffff, v11
	v_and_b32_e32 v24, 0x7fffffff, v10
	v_pk_mul_f32 v[22:23], v[38:39], v[6:7]
	v_and_b32_e32 v7, 0x7fffffff, v19
	v_and_b32_e32 v6, 0x7fffffff, v18
	v_cndmask_b32_e32 v46, v195, v46, vcc
	v_pk_add_f32 v[14:15], v[24:25], v[14:15]
	v_and_b32_e32 v25, 0x7fffffff, v9
	v_and_b32_e32 v24, 0x7fffffff, v8
	v_pk_add_f32 v[6:7], v[6:7], v[16:17]
	v_and_b32_e32 v13, 0x7fffffff, v23
	v_and_b32_e32 v12, 0x7fffffff, v22
	v_lshlrev_b32_e32 v46, 2, v46
	v_pk_add_f32 v[14:15], v[24:25], v[14:15]
	v_pk_add_f32 v[6:7], v[12:13], v[6:7]
	ds_bpermute_b32 v24, v46, v14
	ds_bpermute_b32 v25, v46, v15
	ds_bpermute_b32 v12, v46, v6
	ds_bpermute_b32 v13, v46, v7
	v_xor_b32_e32 v47, 16, v195
	v_cmp_lt_i32_e32 vcc, v47, v1
	s_waitcnt lgkmcnt(2)
	v_pk_add_f32 v[14:15], v[14:15], v[24:25]
	v_xor_b32_e32 v48, 8, v195
	v_cndmask_b32_e32 v47, v195, v47, vcc
	v_lshlrev_b32_e32 v47, 2, v47
	s_waitcnt lgkmcnt(0)
	v_pk_add_f32 v[6:7], v[6:7], v[12:13]
	ds_bpermute_b32 v24, v47, v14
	ds_bpermute_b32 v25, v47, v15
	ds_bpermute_b32 v12, v47, v6
	ds_bpermute_b32 v13, v47, v7
	v_cmp_lt_i32_e32 vcc, v48, v1
	v_xor_b32_e32 v49, 4, v195
	s_waitcnt lgkmcnt(2)
	v_pk_add_f32 v[14:15], v[14:15], v[24:25]
	v_cndmask_b32_e32 v48, v195, v48, vcc
	v_lshlrev_b32_e32 v48, 2, v48
	s_waitcnt lgkmcnt(0)
	v_pk_add_f32 v[6:7], v[6:7], v[12:13]
	ds_bpermute_b32 v16, v48, v14
	ds_bpermute_b32 v17, v48, v15
	ds_bpermute_b32 v12, v48, v6
	ds_bpermute_b32 v13, v48, v7
	v_cmp_lt_i32_e32 vcc, v49, v1
	v_xor_b32_e32 v50, 2, v195
	s_waitcnt lgkmcnt(2)
	v_pk_add_f32 v[14:15], v[14:15], v[16:17]
	v_cndmask_b32_e32 v49, v195, v49, vcc
	v_lshlrev_b32_e32 v49, 2, v49
	s_waitcnt lgkmcnt(0)
	v_pk_add_f32 v[6:7], v[6:7], v[12:13]
	ds_bpermute_b32 v16, v49, v14
	ds_bpermute_b32 v17, v49, v15
	ds_bpermute_b32 v24, v49, v6
	ds_bpermute_b32 v25, v49, v7
	s_mov_b64 s[42:43], 0x3c00
	v_cmp_lt_i32_e32 vcc, v50, v1
	v_lshl_add_u64 v[20:21], v[134:135], 0, s[42:43]
	v_lshl_add_u64 v[26:27], v[20:21], 0, s[24:25]
	v_cndmask_b32_e32 v50, v195, v50, vcc
	v_lshl_add_u64 v[30:31], v[20:21], 0, s[0:1]
	v_lshl_add_u64 v[32:33], v[20:21], 0, s[22:23]
	v_lshlrev_b32_e32 v28, 2, v50
	s_waitcnt lgkmcnt(2)
	v_pk_add_f32 v[14:15], v[14:15], v[16:17]
	s_waitcnt lgkmcnt(0)
	v_pk_add_f32 v[6:7], v[6:7], v[24:25]
	v_lshl_add_u64 v[36:37], v[20:21], 0, s[28:29]
	global_store_dword v[26:27], v10, off
	global_store_dword v[30:31], v8, off
	ds_bpermute_b32 v16, v28, v14
	ds_bpermute_b32 v17, v28, v15
	global_store_dword v[32:33], v11, off
	global_store_dword v[36:37], v9, off
	ds_bpermute_b32 v8, v28, v6
	ds_bpermute_b32 v9, v28, v7
	v_xor_b32_e32 v29, 1, v195
	v_cmp_lt_i32_e32 vcc, v29, v1
	s_waitcnt lgkmcnt(2)
	v_pk_add_f32 v[10:11], v[14:15], v[16:17]
	v_lshl_add_u64 v[40:41], v[20:21], 0, s[34:35]
	v_cndmask_b32_e32 v1, v195, v29, vcc
	v_lshlrev_b32_e32 v1, 2, v1
	s_waitcnt lgkmcnt(0)
	v_pk_add_f32 v[6:7], v[6:7], v[8:9]
	ds_bpermute_b32 v12, v1, v10
	ds_bpermute_b32 v13, v1, v11
	ds_bpermute_b32 v8, v1, v6
	ds_bpermute_b32 v9, v1, v7
	v_and_b32_e32 v1, 63, v2
	v_lshl_add_u64 v[42:43], v[20:21], 0, s[36:37]
	v_lshl_add_u64 v[44:45], v[20:21], 0, s[38:39]
	v_lshl_add_u64 v[20:21], v[20:21], 0, s[40:41]
	v_cmp_eq_u32_e64 s[0:1], 0, v1
	s_movk_i32 s43, 0x1fff
	global_store_dword v[40:41], v18, off
	global_store_dword v[42:43], v22, off
	global_store_dword v[44:45], v19, off
	global_store_dword v[20:21], v23, off
	s_branch .LBB0_1106

	.amdhsa_kernel _Z4mega6Paramsii
		.amdhsa_group_segment_fixed_size 73744
		.amdhsa_private_segment_fixed_size 0
		.amdhsa_kernarg_size 512
		.amdhsa_user_sgpr_count 2
		.amdhsa_user_sgpr_dispatch_ptr 0
		.amdhsa_user_sgpr_queue_ptr 0
		.amdhsa_user_sgpr_kernarg_segment_ptr 1
		.amdhsa_user_sgpr_dispatch_id 0
		.amdhsa_user_sgpr_kernarg_preload_length 0
		.amdhsa_user_sgpr_kernarg_preload_offset 0
		.amdhsa_user_sgpr_private_segment_size 0
		.amdhsa_uses_dynamic_stack 0
		.amdhsa_enable_private_segment 0
		.amdhsa_system_sgpr_workgroup_id_x 1
		.amdhsa_system_sgpr_workgroup_id_y 0
		.amdhsa_system_sgpr_workgroup_id_z 0
		.amdhsa_system_sgpr_workgroup_info 0
		.amdhsa_system_vgpr_workitem_id 2
		.amdhsa_next_free_vgpr 256
		.amdhsa_next_free_sgpr 102
		.amdhsa_accum_offset 256
		.amdhsa_reserve_vcc 1
		.amdhsa_float_round_mode_32 0
		.amdhsa_float_round_mode_16_64 0
		.amdhsa_float_denorm_mode_32 3
		.amdhsa_float_denorm_mode_16_64 3
		.amdhsa_dx10_clamp 1
		.amdhsa_ieee_mode 1
		.amdhsa_fp16_overflow 0
		.amdhsa_tg_split 0
		.amdhsa_exception_fp_ieee_invalid_op 0
		.amdhsa_exception_fp_denorm_src 0
		.amdhsa_exception_fp_ieee_div_zero 0
		.amdhsa_exception_fp_ieee_overflow 0
		.amdhsa_exception_fp_ieee_underflow 0
		.amdhsa_exception_fp_ieee_inexact 0
		.amdhsa_exception_int_div_zero 0
	.end_amdhsa_kernel

amdhsa.kernels:
  - .agpr_count:     0
    .args:
      - .offset:         0
        .size:           248
        .value_kind:     by_value
      - .offset:         248
        .size:           4
        .value_kind:     by_value
      - .offset:         252
        .size:           4
        .value_kind:     by_value
      - .offset:         256
        .size:           4
        .value_kind:     hidden_block_count_x
      - .offset:         260
        .size:           4
        .value_kind:     hidden_block_count_y
      - .offset:         264
        .size:           4
        .value_kind:     hidden_block_count_z
      - .offset:         268
        .size:           2
        .value_kind:     hidden_group_size_x
      - .offset:         270
        .size:           2
        .value_kind:     hidden_group_size_y
      - .offset:         272
        .size:           2
        .value_kind:     hidden_group_size_z
      - .offset:         274
        .size:           2
        .value_kind:     hidden_remainder_x
      - .offset:         276
        .size:           2
        .value_kind:     hidden_remainder_y
      - .offset:         278
        .size:           2
        .value_kind:     hidden_remainder_z
      - .offset:         296
        .size:           8
        .value_kind:     hidden_global_offset_x
      - .offset:         304
        .size:           8
        .value_kind:     hidden_global_offset_y
      - .offset:         312
        .size:           8
        .value_kind:     hidden_global_offset_z
      - .offset:         320
        .size:           2
        .value_kind:     hidden_grid_dims
      - .offset:         344
        .size:           8
        .value_kind:     hidden_multigrid_sync_arg
    .group_segment_fixed_size: 73744
    .kernarg_segment_align: 8
    .kernarg_segment_size: 512
    .language:       OpenCL C
    .language_version:
      - 2
      - 0
    .max_flat_workgroup_size: 256
    .name:           _Z4mega6Paramsii
    .private_segment_fixed_size: 0
    .sgpr_count:     108
    .sgpr_spill_count: 283
    .symbol:         _Z4mega6Paramsii.kd
    .uniform_work_group_size: 1
    .uses_dynamic_stack: false
    .vgpr_count:     256
    .vgpr_spill_count: 0
    .wavefront_size: 64
